# scan: decay constant of the next call no longer waited for inside the prefetch block (scaled at the top of the next body)
# baseline (speedup 1.0000x reference)
; __device__ __forceinline__ float bf2f(bf16_t b) { return __uint_as_float(((unsigned)b) << 16); }
; __device__ __forceinline__ float fast_sigmoid(float x) { return __builtin_amdgcn_rcpf(1.0f + __builtin_amdgcn_exp2f(-1.4426950408889634f * x)); }
; template <int DIR>
; __device__ __forceinline__ void scan_dir(PP p, const bf16_t* xs, const ScanW& w, ScanW& wn, int ndir, int nct, bool do_next, int n, int ct, int l31, int hl, int id, int rowbase, bool latent, float (&hf)[2][16]) {
;     ...
;     for (int rt = 0; rt < 2; ++rt) {
;         bf16x8 af[4];
; #pragma unroll
;         for (int st = 0; st < 4; ++st) af[st] = *(const bf16x8*)(xs + (32 * rt + l31) * XS + 64 * n + 16 * st + 8 * hl);
;         f32x16 ga, gi;
; #pragma unroll
;         for (int i = 0; i < 16; ++i) { ga[i] = 0.f; gi[i] = 0.f; }
; #pragma unroll
;         for (int st = 0; st < 4; ++st) { ga = __builtin_amdgcn_mfma_f32_32x32x16_bf16(af[st], wfa[st], ga, 0, 0, 0); gi = __builtin_amdgcn_mfma_f32_32x32x16_bf16(af[st], wfi[st], gi, 0, 0, 0); }
; #pragma unroll
;         for (int i = 0; i < 16; ++i) {
;             const int token = 32 * rt + 8 * (i >> 2) + 4 * hl + (i & 3);
;             const float xv = bf2f(xs[token * XS + ch]);
;             const float rr = fast_sigmoid(ga[i] + ba), ii = fast_sigmoid(gi[i] + bi);
;             const float la2 = rr * sp8l2;
;             const float av = __builtin_amdgcn_exp2f(la2);
;             const float t2 = la2 * 1.3862943611f;
;             float em1p = t2 * (1.0f + t2 * (0.5f + t2 * (0.16666667f + t2 * (0.041666668f + t2 * 0.0083333333f)))), em1e = __builtin_fmaf(av, av, -1.0f);
;             asm volatile("" : "+v"(em1p), "+v"(em1e));
;             const float em1 = (t2 > -0.1f) ? em1p : em1e;
;             a[rt][i] = av; u[rt][i] = __builtin_amdgcn_sqrtf(-em1) * (ii * xv);
;         }
.LBB0_378:
	ds_read_b128 v[2:5], v187
	s_lshl_b32 s48, s80, 5
	v_or_b32_e32 v66, s48, v150
	v_lshl_add_u32 v42, v66, 1, 0
	v_add_u32_e32 v0, v42, v151
	ds_read_u16 v43, v0
	ds_read_b128 v[34:37], v187 offset:32
	ds_read_b128 v[38:41], v187 offset:64
	s_waitcnt vmcnt(7) lgkmcnt(3)
	v_mfma_f32_32x32x16_bf16 v[18:33], v[2:5], v[114:117], 0
	s_waitcnt vmcnt(2)
	v_mfma_f32_32x32x16_bf16 v[2:17], v[2:5], v[134:137], 0
	s_waitcnt lgkmcnt(1)
	v_mfma_f32_32x32x16_bf16 v[18:33], v[34:37], v[118:121], v[18:33]
	v_mfma_f32_32x32x16_bf16 v[2:17], v[34:37], v[126:129], v[2:17]
	ds_read_b128 v[34:37], v187 offset:96
	s_waitcnt lgkmcnt(1)
	v_mfma_f32_32x32x16_bf16 v[18:33], v[38:41], v[122:125], v[18:33]
	s_waitcnt vmcnt(1) lgkmcnt(0)
	ds_read_u16 v82, v0 offset:1040
	ds_read_u16 v83, v0 offset:2080
	ds_read_u16 v84, v0 offset:3120
	v_add_u32_e32 v113, v42, v152
	ds_read_u16 v85, v113
	ds_read_u16 v86, v0 offset:9360
	ds_read_u16 v87, v0 offset:10400
	ds_read_u16 v88, v0 offset:11440
	ds_read_u16 v89, v113 offset:8320
	ds_read_u16 v90, v0 offset:17680
	ds_read_u16 v91, v0 offset:18720
	ds_read_u16 v92, v0 offset:19760
	ds_read_u16 v93, v0 offset:34320
	ds_read_u16 v94, v0 offset:35360
	ds_read_u16 v95, v0 offset:36400
	ds_read_u16 v96, v0 offset:41600
	ds_read_u16 v97, v0 offset:42640
	ds_read_u16 v98, v0 offset:43680
	ds_read_u16 v99, v0 offset:44720
	ds_read_u16 v100, v0 offset:49920
	ds_read_u16 v101, v0 offset:50960
	ds_read_u16 v102, v0 offset:52000
	ds_read_u16 v103, v0 offset:53040
	ds_read_u16 v104, v0 offset:58240
	ds_read_u16 v105, v0 offset:59280
	ds_read_u16 v106, v0 offset:60320
	v_mfma_f32_32x32x16_bf16 v[18:33], v[34:37], v[138:141], v[18:33]
	v_mfma_f32_32x32x16_bf16 v[2:17], v[38:41], v[130:133], v[2:17]
	s_nop 10
	v_add_f32_e32 v18, v192, v18
	v_mul_f32_e32 v18, 0xbfb8aa3b, v18
	v_exp_f32_e32 v18, v18
	v_add_f32_e32 v19, v192, v19
	v_mul_f32_e32 v19, 0xbfb8aa3b, v19
	v_exp_f32_e32 v19, v19
	v_add_f32_e32 v18, 1.0, v18
	s_waitcnt vmcnt(0)
	v_mfma_f32_32x32x16_bf16 v[2:17], v[34:37], v[142:145], v[2:17]
	v_rcp_f32_e32 v18, v18
	v_add_f32_e32 v19, 1.0, v19
	v_rcp_f32_e32 v19, v19
	v_lshlrev_b32_e32 v34, 16, v43
	v_mul_f32_e32 v18, v194, v18
	v_exp_f32_e32 v50, v18
	v_mul_f32_e32 v18, 0x3fb17218, v18
	s_nop 4
	v_add_f32_e32 v2, v191, v2
	v_mul_f32_e32 v2, 0xbfb8aa3b, v2
	v_exp_f32_e32 v2, v2
	v_fmamk_f32 v35, v18, 0x3c088888, v186
	v_fmaak_f32 v35, v18, v35, 0x3e2aaaab
	v_fma_f32 v35, v18, v35, 0.5
	v_add_f32_e32 v2, 1.0, v2
	v_add_f32_e32 v3, v191, v3
	v_rcp_f32_e32 v2, v2
	v_fma_f32 v35, v18, v35, 1.0
	v_mul_f32_e32 v3, 0xbfb8aa3b, v3
	v_mul_f32_e32 v35, v18, v35
	v_fma_f32 v36, v50, v50, -1.0
	v_exp_f32_e32 v3, v3
	v_mul_f32_e32 v19, v194, v19
	v_cmp_lt_f32_e32 vcc, s76, v18
	v_exp_f32_e32 v52, v19
	v_mul_f32_e32 v19, 0x3fb17218, v19
	v_cndmask_b32_e32 v18, v36, v35, vcc
	v_fmamk_f32 v35, v19, 0x3c088888, v186
	v_mul_f32_e32 v2, v2, v34
	v_fmaak_f32 v35, v19, v35, 0x3e2aaaab
	v_sqrt_f32_e64 v18, -v18
	v_add_f32_e32 v3, 1.0, v3
	v_fma_f32 v35, v19, v35, 0.5
	v_add_f32_e32 v4, v191, v4
	v_rcp_f32_e32 v3, v3
	v_fma_f32 v35, v19, v35, 1.0
	v_mul_f32_e32 v4, 0xbfb8aa3b, v4
	v_mul_f32_e32 v35, v19, v35
	v_fma_f32 v36, v52, v52, -1.0
	v_cmp_lt_f32_e32 vcc, s76, v19
	v_exp_f32_e32 v4, v4
	v_mul_f32_e32 v2, v2, v18
	v_cndmask_b32_e32 v19, v36, v35, vcc
	v_sqrt_f32_e64 v19, -v19
	s_waitcnt lgkmcnt(0)
	v_lshlrev_b32_e32 v18, 16, v82
	v_mul_f32_e32 v3, v3, v18
	v_add_f32_e32 v4, 1.0, v4
	v_rcp_f32_e32 v4, v4
	v_mul_f32_e32 v3, v3, v19
	v_add_f32_e32 v19, v192, v20
	v_mul_f32_e32 v19, 0xbfb8aa3b, v19
	v_exp_f32_e32 v19, v19
	s_waitcnt lgkmcnt(0)
	v_lshlrev_b32_e32 v18, 16, v83
	v_mul_f32_e32 v4, v4, v18
	v_add_f32_e32 v18, v192, v21
	v_mul_f32_e32 v18, 0xbfb8aa3b, v18
	v_exp_f32_e32 v18, v18
	v_add_f32_e32 v19, 1.0, v19
	v_rcp_f32_e32 v19, v19
	v_add_f32_e32 v5, v191, v5
	v_add_f32_e32 v18, 1.0, v18
	v_rcp_f32_e32 v18, v18
	v_mul_f32_e32 v19, v194, v19
	v_exp_f32_e32 v51, v19
	v_mul_f32_e32 v19, 0x3fb17218, v19
	v_fmamk_f32 v20, v19, 0x3c088888, v186
	v_fmaak_f32 v20, v19, v20, 0x3e2aaaab
	v_mul_f32_e32 v18, v194, v18
	v_fma_f32 v20, v19, v20, 0.5
	v_mul_f32_e32 v5, 0xbfb8aa3b, v5
	v_exp_f32_e32 v54, v18
	v_mul_f32_e32 v18, 0x3fb17218, v18
	v_fma_f32 v20, v19, v20, 1.0
	v_exp_f32_e32 v5, v5
	v_fmamk_f32 v21, v18, 0x3c088888, v186
	v_mul_f32_e32 v20, v19, v20
	v_fma_f32 v34, v51, v51, -1.0
	v_fmaak_f32 v21, v18, v21, 0x3e2aaaab
	v_cmp_lt_f32_e32 vcc, s76, v19
	v_fma_f32 v21, v18, v21, 0.5
	v_fma_f32 v21, v18, v21, 1.0
	v_cndmask_b32_e32 v19, v34, v20, vcc
	v_sqrt_f32_e64 v19, -v19
	v_add_f32_e32 v5, 1.0, v5
	v_mul_f32_e32 v21, v18, v21
	v_fma_f32 v34, v54, v54, -1.0
	v_cmp_lt_f32_e32 vcc, s76, v18
	v_rcp_f32_e32 v5, v5
	v_add_f32_e32 v6, v191, v6
	v_cndmask_b32_e32 v18, v34, v21, vcc
	v_sqrt_f32_e64 v18, -v18
	v_mul_f32_e32 v6, 0xbfb8aa3b, v6
	v_mul_f32_e32 v4, v4, v19
	s_waitcnt lgkmcnt(0)
	v_lshlrev_b32_e32 v19, 16, v84
	v_exp_f32_e32 v6, v6
	v_mul_f32_e32 v5, v5, v19
	v_mul_f32_e32 v5, v18, v5
	v_add_u32_e32 v18, v42, v152
	v_add_f32_e32 v20, v192, v22
	v_mul_f32_e32 v20, 0xbfb8aa3b, v20
	v_add_f32_e32 v6, 1.0, v6
	v_exp_f32_e32 v20, v20
	v_rcp_f32_e32 v6, v6
	s_waitcnt lgkmcnt(0)
; __device__ __forceinline__ float bf2f(bf16_t b) { return __uint_as_float(((unsigned)b) << 16); }
; __device__ __forceinline__ float fast_sigmoid(float x) { return __builtin_amdgcn_rcpf(1.0f + __builtin_amdgcn_exp2f(-1.4426950408889634f * x)); }
; template <int DIR>
; __device__ __forceinline__ void scan_dir(PP p, const bf16_t* xs, const ScanW& w, ScanW& wn, int ndir, int nct, bool do_next, int n, int ct, int l31, int hl, int id, int rowbase, bool latent, float (&hf)[2][16]) {
;     ...
;         for (int i = 0; i < 16; ++i) {
;             const int token = 32 * rt + 8 * (i >> 2) + 4 * hl + (i & 3);
;             const float xv = bf2f(xs[token * XS + ch]);
;             const float rr = fast_sigmoid(ga[i] + ba), ii = fast_sigmoid(gi[i] + bi);
;             const float la2 = rr * sp8l2;
;             const float av = __builtin_amdgcn_exp2f(la2);
;             const float t2 = la2 * 1.3862943611f;
;             float em1p = t2 * (1.0f + t2 * (0.5f + t2 * (0.16666667f + t2 * (0.041666668f + t2 * 0.0083333333f)))), em1e = __builtin_fmaf(av, av, -1.0f);
;             asm volatile("" : "+v"(em1p), "+v"(em1e));
;             const float em1 = (t2 > -0.1f) ? em1p : em1e;
;             a[rt][i] = av; u[rt][i] = __builtin_amdgcn_sqrtf(-em1) * (ii * xv);
;         }
	v_lshlrev_b32_e32 v19, 16, v85
	v_add_f32_e32 v7, v191, v7
	v_add_f32_e32 v20, 1.0, v20
	v_mul_f32_e32 v6, v6, v19
	v_add_f32_e32 v19, v192, v23
	v_rcp_f32_e32 v20, v20
	v_mul_f32_e32 v19, 0xbfb8aa3b, v19
	v_exp_f32_e32 v19, v19
	v_mul_f32_e32 v7, 0xbfb8aa3b, v7
	v_mul_f32_e32 v20, v194, v20
	v_exp_f32_e32 v53, v20
	v_mul_f32_e32 v20, 0x3fb17218, v20
	v_add_f32_e32 v19, 1.0, v19
	v_fmamk_f32 v21, v20, 0x3c088888, v186
	v_rcp_f32_e32 v19, v19
	v_fmaak_f32 v21, v20, v21, 0x3e2aaaab
	v_fma_f32 v21, v20, v21, 0.5
	v_fma_f32 v21, v20, v21, 1.0
	v_mul_f32_e32 v21, v20, v21
	v_fma_f32 v22, v53, v53, -1.0
	v_mul_f32_e32 v19, v194, v19
	v_cmp_lt_f32_e32 vcc, s76, v20
	v_exp_f32_e32 v55, v19
	v_mul_f32_e32 v19, 0x3fb17218, v19
	v_cndmask_b32_e32 v20, v22, v21, vcc
	v_exp_f32_e32 v7, v7
	v_fmamk_f32 v22, v19, 0x3c088888, v186
	v_fmaak_f32 v22, v19, v22, 0x3e2aaaab
	v_fma_f32 v22, v19, v22, 0.5
	v_fma_f32 v22, v19, v22, 1.0
	v_sqrt_f32_e64 v20, -v20
	v_add_f32_e32 v7, 1.0, v7
	v_mul_f32_e32 v22, v19, v22
	v_fma_f32 v23, v55, v55, -1.0
	v_cmp_lt_f32_e32 vcc, s76, v19
	v_rcp_f32_e32 v7, v7
	v_add_f32_e32 v8, v191, v8
	v_cndmask_b32_e32 v19, v23, v22, vcc
	v_sqrt_f32_e64 v19, -v19
	v_mul_f32_e32 v8, 0xbfb8aa3b, v8
	v_exp_f32_e32 v8, v8
	v_mul_f32_e32 v6, v20, v6
	s_waitcnt lgkmcnt(0)
	v_lshlrev_b32_e32 v20, 16, v86
	v_mul_f32_e32 v7, v7, v20
	v_mul_f32_e32 v7, v19, v7
	v_add_f32_e32 v20, v192, v24
	v_mul_f32_e32 v20, 0xbfb8aa3b, v20
	v_add_f32_e32 v8, 1.0, v8
	v_exp_f32_e32 v20, v20
	v_rcp_f32_e32 v8, v8
	s_waitcnt lgkmcnt(0)
	v_lshlrev_b32_e32 v19, 16, v87
	v_add_f32_e32 v9, v191, v9
	v_add_f32_e32 v20, 1.0, v20
	v_mul_f32_e32 v8, v8, v19
	v_add_f32_e32 v19, v192, v25
	v_rcp_f32_e32 v20, v20
	v_mul_f32_e32 v19, 0xbfb8aa3b, v19
	v_exp_f32_e32 v19, v19
	v_mul_f32_e32 v9, 0xbfb8aa3b, v9
	v_mul_f32_e32 v20, v194, v20
	v_exp_f32_e32 v67, v20
	v_mul_f32_e32 v20, 0x3fb17218, v20
	v_add_f32_e32 v19, 1.0, v19
	v_fmamk_f32 v21, v20, 0x3c088888, v186
	v_rcp_f32_e32 v19, v19
	v_fmaak_f32 v21, v20, v21, 0x3e2aaaab
	v_fma_f32 v21, v20, v21, 0.5
	v_fma_f32 v21, v20, v21, 1.0
	v_mul_f32_e32 v21, v20, v21
	v_fma_f32 v22, v67, v67, -1.0
	v_mul_f32_e32 v19, v194, v19
	v_cmp_lt_f32_e32 vcc, s76, v20
	v_exp_f32_e32 v69, v19
	v_mul_f32_e32 v19, 0x3fb17218, v19
	v_cndmask_b32_e32 v20, v22, v21, vcc
	v_exp_f32_e32 v9, v9
	v_fmamk_f32 v22, v19, 0x3c088888, v186
	v_fmaak_f32 v22, v19, v22, 0x3e2aaaab
	v_fma_f32 v22, v19, v22, 0.5
	v_fma_f32 v22, v19, v22, 1.0
	v_sqrt_f32_e64 v20, -v20
	v_add_f32_e32 v9, 1.0, v9
	v_mul_f32_e32 v22, v19, v22
	v_fma_f32 v23, v69, v69, -1.0
	v_cmp_lt_f32_e32 vcc, s76, v19
	v_rcp_f32_e32 v9, v9
	v_add_f32_e32 v10, v191, v10
	v_cndmask_b32_e32 v19, v23, v22, vcc
	v_sqrt_f32_e64 v19, -v19
	v_mul_f32_e32 v10, 0xbfb8aa3b, v10
	v_exp_f32_e32 v10, v10
	v_mul_f32_e32 v8, v20, v8
	s_waitcnt lgkmcnt(0)
	v_lshlrev_b32_e32 v20, 16, v88
	v_mul_f32_e32 v9, v9, v20
	v_mul_f32_e32 v76, v19, v9
	v_add_f32_e32 v19, v192, v26
	v_mul_f32_e32 v19, 0xbfb8aa3b, v19
	v_add_f32_e32 v10, 1.0, v10
	v_exp_f32_e32 v19, v19
	v_rcp_f32_e32 v10, v10
	s_waitcnt lgkmcnt(0)
	v_lshlrev_b32_e32 v9, 16, v89
	v_add_f32_e32 v11, v191, v11
	v_add_f32_e32 v19, 1.0, v19
	v_mul_f32_e32 v9, v10, v9
	v_add_f32_e32 v10, v192, v27
	v_rcp_f32_e32 v19, v19
	v_mul_f32_e32 v10, 0xbfb8aa3b, v10
	v_exp_f32_e32 v10, v10
	v_mul_f32_e32 v11, 0xbfb8aa3b, v11
	v_mul_f32_e32 v19, v194, v19
	v_exp_f32_e32 v68, v19
	v_mul_f32_e32 v19, 0x3fb17218, v19
	v_add_f32_e32 v10, 1.0, v10
	v_fmamk_f32 v20, v19, 0x3c088888, v186
	v_rcp_f32_e32 v10, v10
	v_fmaak_f32 v20, v19, v20, 0x3e2aaaab
	v_fma_f32 v20, v19, v20, 0.5
	v_fma_f32 v20, v19, v20, 1.0
	v_mul_f32_e32 v20, v19, v20
	v_fma_f32 v21, v68, v68, -1.0
	v_mul_f32_e32 v10, v194, v10
	v_cmp_lt_f32_e32 vcc, s76, v19
	v_exp_f32_e32 v71, v10
	v_mul_f32_e32 v10, 0x3fb17218, v10
	v_cndmask_b32_e32 v19, v21, v20, vcc
	v_exp_f32_e32 v11, v11
	v_fmamk_f32 v21, v10, 0x3c088888, v186
	v_fmaak_f32 v21, v10, v21, 0x3e2aaaab
	v_fma_f32 v21, v10, v21, 0.5
	v_fma_f32 v21, v10, v21, 1.0
	v_sqrt_f32_e64 v19, -v19
	v_add_f32_e32 v11, 1.0, v11
	v_mul_f32_e32 v21, v10, v21
	v_fma_f32 v22, v71, v71, -1.0
	v_cmp_lt_f32_e32 vcc, s76, v10
	v_rcp_f32_e32 v11, v11
	v_mul_f32_e32 v74, v19, v9
	v_cndmask_b32_e32 v10, v22, v21, vcc
	v_sqrt_f32_e64 v10, -v10
	s_waitcnt lgkmcnt(0)
	v_lshlrev_b32_e32 v9, 16, v90
	v_mul_f32_e32 v9, v11, v9
	v_add_f32_e32 v11, v191, v12
	v_mul_f32_e32 v73, v10, v9
	v_add_f32_e32 v10, v192, v28
	v_mul_f32_e32 v10, 0xbfb8aa3b, v10
	v_exp_f32_e32 v10, v10
	v_mul_f32_e32 v11, 0xbfb8aa3b, v11
	v_exp_f32_e32 v11, v11
	v_add_f32_e32 v10, 1.0, v10
	v_rcp_f32_e32 v10, v10
	s_waitcnt lgkmcnt(0)
; __device__ __forceinline__ float bf2f(bf16_t b) { return __uint_as_float(((unsigned)b) << 16); }
; __device__ __forceinline__ float fast_sigmoid(float x) { return __builtin_amdgcn_rcpf(1.0f + __builtin_amdgcn_exp2f(-1.4426950408889634f * x)); }
; template <int DIR>
; __device__ __forceinline__ void scan_dir(PP p, const bf16_t* xs, const ScanW& w, ScanW& wn, int ndir, int nct, bool do_next, int n, int ct, int l31, int hl, int id, int rowbase, bool latent, float (&hf)[2][16]) {
;     ...
;     for (int rt = 0; rt < 2; ++rt) {
;         bf16x8 af[4];
; #pragma unroll
;         for (int st = 0; st < 4; ++st) af[st] = *(const bf16x8*)(xs + (32 * rt + l31) * XS + 64 * n + 16 * st + 8 * hl);
;         f32x16 ga, gi;
; #pragma unroll
;         for (int i = 0; i < 16; ++i) { ga[i] = 0.f; gi[i] = 0.f; }
; #pragma unroll
;         for (int st = 0; st < 4; ++st) { ga = __builtin_amdgcn_mfma_f32_32x32x16_bf16(af[st], wfa[st], ga, 0, 0, 0); gi = __builtin_amdgcn_mfma_f32_32x32x16_bf16(af[st], wfi[st], gi, 0, 0, 0); }
; #pragma unroll
;         for (int i = 0; i < 16; ++i) {
;             const int token = 32 * rt + 8 * (i >> 2) + 4 * hl + (i & 3);
;             const float xv = bf2f(xs[token * XS + ch]);
;             const float rr = fast_sigmoid(ga[i] + ba), ii = fast_sigmoid(gi[i] + bi);
;             const float la2 = rr * sp8l2;
;             const float av = __builtin_amdgcn_exp2f(la2);
;             const float t2 = la2 * 1.3862943611f;
;             float em1p = t2 * (1.0f + t2 * (0.5f + t2 * (0.16666667f + t2 * (0.041666668f + t2 * 0.0083333333f)))), em1e = __builtin_fmaf(av, av, -1.0f);
;             asm volatile("" : "+v"(em1p), "+v"(em1e));
;             const float em1 = (t2 > -0.1f) ? em1p : em1e;
;             a[rt][i] = av; u[rt][i] = __builtin_amdgcn_sqrtf(-em1) * (ii * xv);
;         }
	v_lshlrev_b32_e32 v9, 16, v91
	v_add_f32_e32 v11, 1.0, v11
	v_rcp_f32_e32 v11, v11
	v_mul_f32_e32 v10, v194, v10
	v_exp_f32_e32 v70, v10
	v_mul_f32_e32 v10, 0x3fb17218, v10
	v_fmamk_f32 v12, v10, 0x3c088888, v186
	v_fmaak_f32 v12, v10, v12, 0x3e2aaaab
	v_fma_f32 v12, v10, v12, 0.5
	v_fma_f32 v12, v10, v12, 1.0
	v_mul_f32_e32 v12, v10, v12
	v_fma_f32 v19, v70, v70, -1.0
	v_cmp_lt_f32_e32 vcc, s76, v10
	v_mul_f32_e32 v9, v11, v9
	v_add_f32_e32 v11, v191, v13
	v_cndmask_b32_e32 v10, v19, v12, vcc
	v_add_f32_e32 v12, v192, v29
	v_mul_f32_e32 v12, 0xbfb8aa3b, v12
	v_exp_f32_e32 v12, v12
	v_sqrt_f32_e64 v19, -v10
	v_mul_f32_e32 v11, 0xbfb8aa3b, v11
	v_exp_f32_e32 v21, v11
	v_add_f32_e32 v10, 1.0, v12
	v_rcp_f32_e32 v10, v10
	v_add_f32_e32 v11, v192, v30
	v_mul_f32_e32 v11, 0xbfb8aa3b, v11
	v_exp_f32_e32 v11, v11
	v_mul_f32_e32 v10, v194, v10
	v_mul_f32_e32 v22, 0x3fb17218, v10
	v_exp_f32_e32 v75, v10
	v_fmamk_f32 v10, v22, 0x3c088888, v186
	v_fmaak_f32 v10, v22, v10, 0x3e2aaaab
	v_fma_f32 v10, v22, v10, 0.5
	v_fma_f32 v10, v22, v10, 1.0
	v_mul_f32_e32 v23, v22, v10
	v_add_f32_e32 v10, 1.0, v11
	v_rcp_f32_e32 v10, v10
	v_add_f32_e32 v11, v192, v31
	v_mul_f32_e32 v11, 0xbfb8aa3b, v11
	v_exp_f32_e32 v11, v11
	v_mul_f32_e32 v10, v194, v10
	v_mul_f32_e32 v60, 0x3fb17218, v10
	v_exp_f32_e32 v72, v10
	v_fmamk_f32 v10, v60, 0x3c088888, v186
	v_fmaak_f32 v10, v60, v10, 0x3e2aaaab
	v_fma_f32 v10, v60, v10, 0.5
	v_fma_f32 v10, v60, v10, 1.0
	v_mul_f32_e32 v61, v60, v10
	v_add_f32_e32 v10, 1.0, v11
	v_rcp_f32_e32 v10, v10
	v_add_f32_e32 v11, v192, v32
	v_mul_f32_e32 v11, 0xbfb8aa3b, v11
	v_exp_f32_e32 v11, v11
	v_mul_f32_e32 v10, v194, v10
	v_mul_f32_e32 v64, 0x3fb17218, v10
	v_exp_f32_e32 v78, v10
	v_fmamk_f32 v10, v64, 0x3c088888, v186
	v_fmaak_f32 v10, v64, v10, 0x3e2aaaab
	v_fma_f32 v10, v64, v10, 0.5
	v_fma_f32 v10, v64, v10, 1.0
	v_mul_f32_e32 v65, v64, v10
	v_add_f32_e32 v10, 1.0, v11
	v_rcp_f32_e32 v10, v10
	v_add_f32_e32 v11, v192, v33
	v_mul_f32_e32 v11, 0xbfb8aa3b, v11
	v_exp_f32_e32 v11, v11
	v_mul_f32_e32 v10, v194, v10
	v_mul_f32_e32 v146, 0x3fb17218, v10
	v_exp_f32_e32 v77, v10
	v_fmamk_f32 v10, v146, 0x3c088888, v186
	v_fmaak_f32 v10, v146, v10, 0x3e2aaaab
	v_fma_f32 v10, v146, v10, 0.5
	v_fma_f32 v10, v146, v10, 1.0
	v_mul_f32_e32 v147, v146, v10
	v_add_f32_e32 v10, 1.0, v11
	v_rcp_f32_e32 v10, v10
	v_fma_f32 v24, v75, v75, -1.0
	v_mul_f32_e32 v209, v19, v9
	v_mul_f32_e32 v10, v194, v10
	v_mul_f32_e32 v156, 0x3fb17218, v10
	v_add_f32_e32 v19, 1.0, v21
	v_cmp_lt_f32_e32 vcc, s76, v22
	v_exp_f32_e32 v79, v10
	v_fmamk_f32 v10, v156, 0x3c088888, v186
	v_rcp_f32_e32 v35, v19
	v_cndmask_b32_e32 v19, v24, v23, vcc
	v_fmaak_f32 v10, v156, v10, 0x3e2aaaab
	v_sqrt_f32_e64 v36, -v19
	v_fma_f32 v10, v156, v10, 0.5
	v_fma_f32 v10, v156, v10, 1.0
	s_waitcnt lgkmcnt(0)
	v_lshlrev_b32_e32 v9, 16, v92
	v_fma_f32 v62, v72, v72, -1.0
	v_fma_f32 v80, v78, v78, -1.0
	v_fma_f32 v154, v77, v77, -1.0
	v_mul_f32_e32 v158, v156, v10
	v_fma_f32 v159, v79, v79, -1.0
	v_mul_f32_e32 v9, v35, v9
	ds_read_u16 v34, v18 offset:16640
	ds_read_u16 v63, v0 offset:26000
	ds_read_u16 v81, v0 offset:27040
	ds_read_u16 v155, v0 offset:28080
	ds_read_b128 v[10:13], v187 offset:33280
	ds_read_u16 v195, v18 offset:24960
	v_mul_f32_e32 v217, v36, v9
	v_add_f32_e32 v9, v191, v14
	v_mul_f32_e32 v9, 0xbfb8aa3b, v9
	v_exp_f32_e32 v9, v9
	v_add_f32_e32 v15, v191, v15
	v_mul_f32_e32 v15, 0xbfb8aa3b, v15
	v_exp_f32_e32 v15, v15
	v_add_f32_e32 v9, 1.0, v9
	v_rcp_f32_e32 v9, v9
	ds_read_b128 v[56:59], v187 offset:33312
	s_waitcnt lgkmcnt(6)
	v_lshlrev_b32_e32 v14, 16, v34
	s_waitcnt lgkmcnt(2)
	v_mfma_f32_32x32x16_bf16 v[34:49], v[10:13], v[134:137], 0
	v_cmp_lt_f32_e32 vcc, s76, v60
	v_mul_f32_e32 v9, v9, v14
	v_add_f32_e32 v14, 1.0, v15
	v_rcp_f32_e32 v14, v14
	v_mfma_f32_32x32x16_bf16 v[18:33], v[10:13], v[114:117], 0
	v_cndmask_b32_e32 v10, v62, v61, vcc
	v_sqrt_f32_e64 v60, -v10
	ds_read_b128 v[10:13], v187 offset:33344
	v_cmp_lt_f32_e32 vcc, s76, v64
	v_mul_f32_e32 v197, v60, v9
	v_lshlrev_b32_e32 v9, 16, v63
	v_mul_f32_e32 v9, v14, v9
	v_add_f32_e32 v14, v191, v16
	s_waitcnt lgkmcnt(1)
	v_mfma_f32_32x32x16_bf16 v[34:49], v[56:59], v[126:129], v[34:49]
	v_mul_f32_e32 v14, 0xbfb8aa3b, v14
	v_exp_f32_e32 v14, v14
	v_cndmask_b32_e32 v15, v80, v65, vcc
	v_sqrt_f32_e64 v15, -v15
	v_cmp_lt_f32_e32 vcc, s76, v146
	v_add_f32_e32 v14, 1.0, v14
	v_mul_f32_e32 v199, v15, v9
	v_mfma_f32_32x32x16_bf16 v[18:33], v[56:59], v[118:121], v[18:33]
	v_rcp_f32_e32 v56, v14
	v_add_f32_e32 v14, v191, v17
	v_mul_f32_e32 v57, 0xbfb8aa3b, v14
	ds_read_b128 v[14:17], v187 offset:33376
	v_lshlrev_b32_e32 v9, 16, v81
	v_mul_f32_e32 v9, v56, v9
	s_waitcnt lgkmcnt(1)
	v_mfma_f32_32x32x16_bf16 v[34:49], v[10:13], v[130:133], v[34:49]
	v_mfma_f32_32x32x16_bf16 v[18:33], v[10:13], v[122:125], v[18:33]
	v_exp_f32_e32 v10, v57
	v_cndmask_b32_e32 v11, v154, v147, vcc
	v_sqrt_f32_e64 v11, -v11
	v_cmp_lt_f32_e32 vcc, s76, v156
	v_add_f32_e32 v10, 1.0, v10
	v_rcp_f32_e32 v10, v10
	v_cndmask_b32_e32 v12, v159, v158, vcc
	s_waitcnt lgkmcnt(0)
; __device__ __forceinline__ float bf2f(bf16_t b) { return __uint_as_float(((unsigned)b) << 16); }
; __device__ __forceinline__ float fast_sigmoid(float x) { return __builtin_amdgcn_rcpf(1.0f + __builtin_amdgcn_exp2f(-1.4426950408889634f * x)); }
; template <int DIR>
; __device__ __forceinline__ void scan_dir(PP p, const bf16_t* xs, const ScanW& w, ScanW& wn, int ndir, int nct, bool do_next, int n, int ct, int l31, int hl, int id, int rowbase, bool latent, float (&hf)[2][16]) {
;     ...
;         for (int i = 0; i < 16; ++i) {
;             const int token = 32 * rt + 8 * (i >> 2) + 4 * hl + (i & 3);
;             const float xv = bf2f(xs[token * XS + ch]);
;             const float rr = fast_sigmoid(ga[i] + ba), ii = fast_sigmoid(gi[i] + bi);
;             const float la2 = rr * sp8l2;
;             const float av = __builtin_amdgcn_exp2f(la2);
;             const float t2 = la2 * 1.3862943611f;
;             float em1p = t2 * (1.0f + t2 * (0.5f + t2 * (0.16666667f + t2 * (0.041666668f + t2 * 0.0083333333f)))), em1e = __builtin_fmaf(av, av, -1.0f);
;             asm volatile("" : "+v"(em1p), "+v"(em1e));
;             const float em1 = (t2 > -0.1f) ? em1p : em1e;
;             a[rt][i] = av; u[rt][i] = __builtin_amdgcn_sqrtf(-em1) * (ii * xv);
;         }
	v_mfma_f32_32x32x16_bf16 v[34:49], v[14:17], v[142:145], v[34:49]
	v_sqrt_f32_e64 v12, -v12
	v_mul_f32_e32 v204, v11, v9
	v_lshlrev_b32_e32 v9, 16, v155
	v_mul_f32_e32 v9, v10, v9
	v_mul_f32_e32 v202, v12, v9
	v_lshlrev_b32_e32 v11, 16, v195
	s_nop 5
	v_add_f32_e32 v10, v191, v34
	v_mfma_f32_32x32x16_bf16 v[18:33], v[14:17], v[138:141], v[18:33]
	v_mul_f32_e32 v10, 0xbfb8aa3b, v10
	v_exp_f32_e32 v10, v10
	s_nop 0
	v_add_f32_e32 v10, 1.0, v10
	v_rcp_f32_e32 v10, v10
	s_nop 6
	v_add_f32_e32 v9, v192, v18
	v_mul_f32_e32 v9, 0xbfb8aa3b, v9
	v_exp_f32_e32 v9, v9
	v_mul_f32_e32 v10, v10, v11
	v_add_f32_e32 v11, v192, v19
	v_mul_f32_e32 v11, 0xbfb8aa3b, v11
	v_add_f32_e32 v9, 1.0, v9
	v_rcp_f32_e32 v9, v9
	v_exp_f32_e32 v11, v11
	v_mul_f32_e32 v9, v194, v9
	v_exp_f32_e32 v80, v9
	v_mul_f32_e32 v9, 0x3fb17218, v9
	v_fmamk_f32 v12, v9, 0x3c088888, v186
	v_fmaak_f32 v12, v9, v12, 0x3e2aaaab
	v_add_f32_e32 v11, 1.0, v11
	v_fma_f32 v12, v9, v12, 0.5
	v_rcp_f32_e32 v11, v11
	v_fma_f32 v12, v9, v12, 1.0
	v_mul_f32_e32 v12, v9, v12
	v_fma_f32 v13, v80, v80, -1.0
	v_cmp_lt_f32_e32 vcc, s76, v9
	v_mul_f32_e32 v11, v194, v11
	v_exp_f32_e32 v146, v11
	v_cndmask_b32_e32 v9, v13, v12, vcc
	v_add_f32_e32 v12, v191, v35
	v_mul_f32_e32 v12, 0xbfb8aa3b, v12
	v_mul_f32_e32 v11, 0x3fb17218, v11
	v_exp_f32_e32 v12, v12
	v_fmamk_f32 v14, v11, 0x3c088888, v186
	v_fmaak_f32 v14, v11, v14, 0x3e2aaaab
	v_fma_f32 v14, v11, v14, 0.5
	v_fma_f32 v14, v11, v14, 1.0
	v_sqrt_f32_e64 v9, -v9
	v_add_f32_e32 v12, 1.0, v12
	v_mul_f32_e32 v14, v11, v14
	v_fma_f32 v15, v146, v146, -1.0
	v_cmp_lt_f32_e32 vcc, s76, v11
	v_rcp_f32_e32 v12, v12
	v_mul_f32_e32 v196, v10, v9
	v_cndmask_b32_e32 v11, v15, v14, vcc
	v_sqrt_f32_e64 v11, -v11
	s_waitcnt lgkmcnt(0)
	v_lshlrev_b32_e32 v9, 16, v93
	v_mul_f32_e32 v9, v12, v9
	v_add_f32_e32 v10, v192, v20
	v_mul_f32_e32 v195, v9, v11
	v_add_f32_e32 v11, v191, v36
	v_mul_f32_e32 v11, 0xbfb8aa3b, v11
	v_exp_f32_e32 v11, v11
	v_mul_f32_e32 v10, 0xbfb8aa3b, v10
	v_exp_f32_e32 v10, v10
	v_add_f32_e32 v11, 1.0, v11
	v_rcp_f32_e32 v11, v11
	v_add_f32_e32 v10, 1.0, v10
	v_rcp_f32_e32 v10, v10
	s_waitcnt lgkmcnt(0)
	v_lshlrev_b32_e32 v9, 16, v94
	v_mul_f32_e32 v9, v11, v9
	v_add_f32_e32 v11, v192, v21
	v_mul_f32_e32 v11, 0xbfb8aa3b, v11
	v_exp_f32_e32 v11, v11
	v_mul_f32_e32 v10, v194, v10
	v_exp_f32_e32 v81, v10
	v_mul_f32_e32 v10, 0x3fb17218, v10
	v_fmamk_f32 v12, v10, 0x3c088888, v186
	v_fmaak_f32 v12, v10, v12, 0x3e2aaaab
	v_add_f32_e32 v11, 1.0, v11
	v_fma_f32 v12, v10, v12, 0.5
	v_rcp_f32_e32 v11, v11
	v_fma_f32 v12, v10, v12, 1.0
	v_mul_f32_e32 v12, v10, v12
	v_fma_f32 v13, v81, v81, -1.0
	v_cmp_lt_f32_e32 vcc, s76, v10
	v_mul_f32_e32 v11, v194, v11
	v_exp_f32_e32 v198, v11
	v_cndmask_b32_e32 v10, v13, v12, vcc
	v_add_f32_e32 v12, v191, v37
	v_mul_f32_e32 v12, 0xbfb8aa3b, v12
	v_mul_f32_e32 v11, 0x3fb17218, v11
	v_exp_f32_e32 v12, v12
	v_fmamk_f32 v14, v11, 0x3c088888, v186
	v_fmaak_f32 v14, v11, v14, 0x3e2aaaab
	v_fma_f32 v14, v11, v14, 0.5
	v_fma_f32 v14, v11, v14, 1.0
	v_sqrt_f32_e64 v10, -v10
	v_add_f32_e32 v12, 1.0, v12
	v_mul_f32_e32 v14, v11, v14
	v_fma_f32 v15, v198, v198, -1.0
	v_cmp_lt_f32_e32 vcc, s76, v11
	v_rcp_f32_e32 v12, v12
	v_mul_f32_e32 v214, v9, v10
	v_cndmask_b32_e32 v11, v15, v14, vcc
	v_sqrt_f32_e64 v11, -v11
	s_waitcnt lgkmcnt(0)
	v_lshlrev_b32_e32 v9, 16, v95
	v_mul_f32_e32 v9, v12, v9
	v_add_f32_e32 v10, v192, v22
	v_mul_f32_e32 v211, v11, v9
	v_add_f32_e32 v11, v191, v38
	v_mul_f32_e32 v11, 0xbfb8aa3b, v11
	v_exp_f32_e32 v11, v11
	v_mul_f32_e32 v10, 0xbfb8aa3b, v10
	v_exp_f32_e32 v10, v10
	v_add_f32_e32 v11, 1.0, v11
	v_rcp_f32_e32 v11, v11
	v_add_f32_e32 v10, 1.0, v10
	v_rcp_f32_e32 v10, v10
	s_waitcnt lgkmcnt(0)
	v_lshlrev_b32_e32 v9, 16, v96
	v_mul_f32_e32 v9, v11, v9
	v_add_f32_e32 v11, v192, v23
	v_mul_f32_e32 v11, 0xbfb8aa3b, v11
	v_exp_f32_e32 v11, v11
	v_mul_f32_e32 v10, v194, v10
	v_exp_f32_e32 v147, v10
	v_mul_f32_e32 v10, 0x3fb17218, v10
	v_fmamk_f32 v12, v10, 0x3c088888, v186
	v_fmaak_f32 v12, v10, v12, 0x3e2aaaab
	v_add_f32_e32 v11, 1.0, v11
	v_fma_f32 v12, v10, v12, 0.5
	v_rcp_f32_e32 v11, v11
	v_fma_f32 v12, v10, v12, 1.0
	v_mul_f32_e32 v12, v10, v12
	v_fma_f32 v13, v147, v147, -1.0
	v_cmp_lt_f32_e32 vcc, s76, v10
	v_mul_f32_e32 v11, v194, v11
	v_exp_f32_e32 v201, v11
	v_cndmask_b32_e32 v10, v13, v12, vcc
	v_add_f32_e32 v12, v191, v39
	v_mul_f32_e32 v12, 0xbfb8aa3b, v12
	v_mul_f32_e32 v11, 0x3fb17218, v11
	v_exp_f32_e32 v12, v12
	v_fmamk_f32 v14, v11, 0x3c088888, v186
	v_fmaak_f32 v14, v11, v14, 0x3e2aaaab
	v_fma_f32 v14, v11, v14, 0.5
	v_fma_f32 v14, v11, v14, 1.0
	v_sqrt_f32_e64 v10, -v10
	v_add_f32_e32 v12, 1.0, v12
	v_mul_f32_e32 v14, v11, v14
	v_fma_f32 v15, v201, v201, -1.0
	v_cmp_lt_f32_e32 vcc, s76, v11
	v_rcp_f32_e32 v12, v12
	v_mul_f32_e32 v206, v10, v9
	v_cndmask_b32_e32 v11, v15, v14, vcc
	v_sqrt_f32_e64 v11, -v11
	s_waitcnt lgkmcnt(0)
	v_lshlrev_b32_e32 v9, 16, v97
	v_mul_f32_e32 v9, v12, v9
	v_add_f32_e32 v10, v192, v24
	v_mul_f32_e32 v205, v11, v9
	v_add_f32_e32 v11, v191, v40
	v_mul_f32_e32 v11, 0xbfb8aa3b, v11
	v_exp_f32_e32 v11, v11
	v_mul_f32_e32 v10, 0xbfb8aa3b, v10
	v_exp_f32_e32 v10, v10
	v_add_f32_e32 v11, 1.0, v11
	v_rcp_f32_e32 v11, v11
	v_add_f32_e32 v10, 1.0, v10
	v_rcp_f32_e32 v10, v10
	s_waitcnt lgkmcnt(0)
; __device__ __forceinline__ float bf2f(bf16_t b) { return __uint_as_float(((unsigned)b) << 16); }
; __device__ __forceinline__ float fast_sigmoid(float x) { return __builtin_amdgcn_rcpf(1.0f + __builtin_amdgcn_exp2f(-1.4426950408889634f * x)); }
; template <int DIR>
; __device__ __forceinline__ void scan_dir(PP p, const bf16_t* xs, const ScanW& w, ScanW& wn, int ndir, int nct, bool do_next, int n, int ct, int l31, int hl, int id, int rowbase, bool latent, float (&hf)[2][16]) {
;     ...
;         for (int i = 0; i < 16; ++i) {
;             const int token = 32 * rt + 8 * (i >> 2) + 4 * hl + (i & 3);
;             const float xv = bf2f(xs[token * XS + ch]);
;             const float rr = fast_sigmoid(ga[i] + ba), ii = fast_sigmoid(gi[i] + bi);
;             const float la2 = rr * sp8l2;
;             const float av = __builtin_amdgcn_exp2f(la2);
;             const float t2 = la2 * 1.3862943611f;
;             float em1p = t2 * (1.0f + t2 * (0.5f + t2 * (0.16666667f + t2 * (0.041666668f + t2 * 0.0083333333f)))), em1e = __builtin_fmaf(av, av, -1.0f);
;             asm volatile("" : "+v"(em1p), "+v"(em1e));
;             const float em1 = (t2 > -0.1f) ? em1p : em1e;
;             a[rt][i] = av; u[rt][i] = __builtin_amdgcn_sqrtf(-em1) * (ii * xv);
;         }
	v_lshlrev_b32_e32 v9, 16, v98
	v_mul_f32_e32 v9, v11, v9
	v_add_f32_e32 v11, v192, v25
	v_mul_f32_e32 v11, 0xbfb8aa3b, v11
	v_exp_f32_e32 v11, v11
	v_mul_f32_e32 v10, v194, v10
	v_exp_f32_e32 v200, v10
	v_mul_f32_e32 v10, 0x3fb17218, v10
	v_fmamk_f32 v12, v10, 0x3c088888, v186
	v_fmaak_f32 v12, v10, v12, 0x3e2aaaab
	v_add_f32_e32 v11, 1.0, v11
	v_fma_f32 v12, v10, v12, 0.5
	v_rcp_f32_e32 v11, v11
	v_fma_f32 v12, v10, v12, 1.0
	v_mul_f32_e32 v12, v10, v12
	v_fma_f32 v13, v200, v200, -1.0
	v_cmp_lt_f32_e32 vcc, s76, v10
	v_mul_f32_e32 v11, v194, v11
	v_exp_f32_e32 v207, v11
	v_cndmask_b32_e32 v10, v13, v12, vcc
	v_add_f32_e32 v12, v191, v41
	v_mul_f32_e32 v12, 0xbfb8aa3b, v12
	v_mul_f32_e32 v11, 0x3fb17218, v11
	v_exp_f32_e32 v12, v12
	v_fmamk_f32 v14, v11, 0x3c088888, v186
	v_fmaak_f32 v14, v11, v14, 0x3e2aaaab
	v_fma_f32 v14, v11, v14, 0.5
	v_fma_f32 v14, v11, v14, 1.0
	v_sqrt_f32_e64 v10, -v10
	v_add_f32_e32 v12, 1.0, v12
	v_mul_f32_e32 v14, v11, v14
	v_fma_f32 v15, v207, v207, -1.0
	v_cmp_lt_f32_e32 vcc, s76, v11
	v_rcp_f32_e32 v12, v12
	v_mul_f32_e32 v222, v10, v9
	v_cndmask_b32_e32 v11, v15, v14, vcc
	v_sqrt_f32_e64 v11, -v11
	s_waitcnt lgkmcnt(0)
	v_lshlrev_b32_e32 v9, 16, v99
	v_mul_f32_e32 v9, v12, v9
	v_add_f32_e32 v10, v192, v26
	v_mul_f32_e32 v221, v11, v9
	v_add_f32_e32 v11, v191, v42
	v_mul_f32_e32 v11, 0xbfb8aa3b, v11
	v_exp_f32_e32 v11, v11
	v_mul_f32_e32 v10, 0xbfb8aa3b, v10
	v_exp_f32_e32 v10, v10
	v_add_f32_e32 v11, 1.0, v11
	v_rcp_f32_e32 v11, v11
	v_add_f32_e32 v10, 1.0, v10
	v_rcp_f32_e32 v10, v10
	s_waitcnt lgkmcnt(0)
	v_lshlrev_b32_e32 v9, 16, v100
	v_mul_f32_e32 v9, v11, v9
	v_add_f32_e32 v11, v192, v27
	v_mul_f32_e32 v11, 0xbfb8aa3b, v11
	v_exp_f32_e32 v11, v11
	v_mul_f32_e32 v10, v194, v10
	v_exp_f32_e32 v203, v10
	v_mul_f32_e32 v10, 0x3fb17218, v10
	v_fmamk_f32 v12, v10, 0x3c088888, v186
	v_fmaak_f32 v12, v10, v12, 0x3e2aaaab
	v_add_f32_e32 v11, 1.0, v11
	v_fma_f32 v12, v10, v12, 0.5
	v_rcp_f32_e32 v11, v11
	v_fma_f32 v12, v10, v12, 1.0
	v_mul_f32_e32 v12, v10, v12
	v_fma_f32 v13, v203, v203, -1.0
	v_cmp_lt_f32_e32 vcc, s76, v10
	v_mul_f32_e32 v11, v194, v11
	v_exp_f32_e32 v210, v11
	v_cndmask_b32_e32 v10, v13, v12, vcc
	v_add_f32_e32 v12, v191, v43
	v_mul_f32_e32 v12, 0xbfb8aa3b, v12
	v_mul_f32_e32 v11, 0x3fb17218, v11
	v_exp_f32_e32 v12, v12
	v_fmamk_f32 v14, v11, 0x3c088888, v186
	v_fmaak_f32 v14, v11, v14, 0x3e2aaaab
	v_fma_f32 v14, v11, v14, 0.5
	v_fma_f32 v14, v11, v14, 1.0
	v_sqrt_f32_e64 v10, -v10
	v_add_f32_e32 v12, 1.0, v12
	v_mul_f32_e32 v14, v11, v14
	v_fma_f32 v15, v210, v210, -1.0
	v_cmp_lt_f32_e32 vcc, s76, v11
	v_rcp_f32_e32 v12, v12
	v_mul_f32_e32 v216, v10, v9
	v_cndmask_b32_e32 v11, v15, v14, vcc
	v_sqrt_f32_e64 v11, -v11
	s_waitcnt lgkmcnt(0)
	v_lshlrev_b32_e32 v9, 16, v101
	v_mul_f32_e32 v9, v12, v9
	v_add_f32_e32 v10, v192, v28
	v_mul_f32_e32 v215, v11, v9
	v_add_f32_e32 v11, v191, v44
	v_mul_f32_e32 v11, 0xbfb8aa3b, v11
	v_exp_f32_e32 v11, v11
	v_mul_f32_e32 v10, 0xbfb8aa3b, v10
	v_exp_f32_e32 v10, v10
	v_add_f32_e32 v11, 1.0, v11
	v_rcp_f32_e32 v11, v11
	v_add_f32_e32 v10, 1.0, v10
	v_rcp_f32_e32 v10, v10
	s_waitcnt lgkmcnt(0)
	v_lshlrev_b32_e32 v9, 16, v102
	v_mul_f32_e32 v9, v11, v9
	v_add_f32_e32 v11, v192, v29
	v_mul_f32_e32 v11, 0xbfb8aa3b, v11
	v_exp_f32_e32 v11, v11
	v_mul_f32_e32 v10, v194, v10
	v_exp_f32_e32 v208, v10
	v_mul_f32_e32 v10, 0x3fb17218, v10
	v_fmamk_f32 v12, v10, 0x3c088888, v186
	v_fmaak_f32 v12, v10, v12, 0x3e2aaaab
	v_add_f32_e32 v11, 1.0, v11
	v_fma_f32 v12, v10, v12, 0.5
	v_rcp_f32_e32 v11, v11
	v_fma_f32 v12, v10, v12, 1.0
	v_mul_f32_e32 v12, v10, v12
	v_fma_f32 v13, v208, v208, -1.0
	v_cmp_lt_f32_e32 vcc, s76, v10
	v_mul_f32_e32 v11, v194, v11
	v_exp_f32_e32 v218, v11
	v_cndmask_b32_e32 v10, v13, v12, vcc
	v_add_f32_e32 v12, v191, v45
	v_mul_f32_e32 v12, 0xbfb8aa3b, v12
	v_mul_f32_e32 v11, 0x3fb17218, v11
	v_exp_f32_e32 v12, v12
	v_fmamk_f32 v14, v11, 0x3c088888, v186
	v_fmaak_f32 v14, v11, v14, 0x3e2aaaab
	v_fma_f32 v14, v11, v14, 0.5
	v_fma_f32 v14, v11, v14, 1.0
	v_sqrt_f32_e64 v10, -v10
	v_add_f32_e32 v12, 1.0, v12
	v_mul_f32_e32 v14, v11, v14
	v_fma_f32 v15, v218, v218, -1.0
	v_cmp_lt_f32_e32 vcc, s76, v11
	v_rcp_f32_e32 v12, v12
	v_mul_f32_e32 v227, v10, v9
	v_cndmask_b32_e32 v11, v15, v14, vcc
	v_sqrt_f32_e64 v11, -v11
	s_waitcnt lgkmcnt(0)
	v_lshlrev_b32_e32 v9, 16, v103
	v_mul_f32_e32 v9, v12, v9
	v_add_f32_e32 v10, v192, v30
	v_mul_f32_e32 v226, v11, v9
	v_add_f32_e32 v11, v191, v46
	v_mul_f32_e32 v11, 0xbfb8aa3b, v11
	v_exp_f32_e32 v11, v11
	v_mul_f32_e32 v10, 0xbfb8aa3b, v10
	v_exp_f32_e32 v10, v10
	v_add_f32_e32 v11, 1.0, v11
	v_rcp_f32_e32 v11, v11
	v_add_f32_e32 v10, 1.0, v10
	v_rcp_f32_e32 v10, v10
	s_waitcnt lgkmcnt(0)
	v_lshlrev_b32_e32 v9, 16, v104
	v_mul_f32_e32 v9, v11, v9
	v_add_f32_e32 v11, v192, v31
	v_mul_f32_e32 v11, 0xbfb8aa3b, v11
	v_exp_f32_e32 v11, v11
	v_mul_f32_e32 v10, v194, v10
	v_exp_f32_e32 v213, v10
	v_mul_f32_e32 v10, 0x3fb17218, v10
	v_fmamk_f32 v12, v10, 0x3c088888, v186
	v_fmaak_f32 v12, v10, v12, 0x3e2aaaab
	v_add_f32_e32 v11, 1.0, v11
	v_fma_f32 v12, v10, v12, 0.5
	v_rcp_f32_e32 v11, v11
	v_fma_f32 v12, v10, v12, 1.0
	v_mul_f32_e32 v12, v10, v12
	v_fma_f32 v13, v213, v213, -1.0
	v_cmp_lt_f32_e32 vcc, s76, v10
	v_mul_f32_e32 v11, v194, v11
	v_exp_f32_e32 v220, v11
	v_cndmask_b32_e32 v10, v13, v12, vcc
	v_add_f32_e32 v12, v191, v47
	v_mul_f32_e32 v12, 0xbfb8aa3b, v12
	v_mul_f32_e32 v11, 0x3fb17218, v11
	v_exp_f32_e32 v12, v12
	v_fmamk_f32 v14, v11, 0x3c088888, v186
	v_fmaak_f32 v14, v11, v14, 0x3e2aaaab
	v_fma_f32 v14, v11, v14, 0.5
	v_fma_f32 v14, v11, v14, 1.0
	v_sqrt_f32_e64 v10, -v10
	v_add_f32_e32 v12, 1.0, v12
	v_mul_f32_e32 v14, v11, v14
	v_fma_f32 v15, v220, v220, -1.0
	v_cmp_lt_f32_e32 vcc, s76, v11
	v_rcp_f32_e32 v12, v12
	v_mul_f32_e32 v224, v10, v9
	v_cndmask_b32_e32 v11, v15, v14, vcc
	v_sqrt_f32_e64 v11, -v11
	s_waitcnt lgkmcnt(0)
; __device__ __forceinline__ float bf2f(bf16_t b) { return __uint_as_float(((unsigned)b) << 16); }
; __device__ __forceinline__ void scan_loadw(PP p, int dir, int n, int ct, int l31, int hl, ScanW& w) {
;     unsigned chv = (unsigned)(32 * ct + l31); asm volatile("" : "+v"(chv));
;     const unsigned ch = (unsigned)(dir * 512 + 64 * n) + chv;
;     w.ba = p->lru_b_a[ch]; w.bi = p->lru_b_i[ch];
;     w.sp8l2 = ((const float*)(p->ws + WS_SP8))[ch] * 1.4426950408889634f;
;     const bf16_t* wa_b = (const bf16_t*)(p->ws + WS_LRU) + (size_t)((dir * 2 + 0) * 8 + n) * 4096;
;     const bf16_t* wi_b = (const bf16_t*)(p->ws + WS_LRU) + (size_t)((dir * 2 + 1) * 8 + n) * 4096;
;     const unsigned lo = chv * 64u + 8u * (unsigned)hl;
; #pragma unroll
;     for (int st = 0; st < 4; ++st) { w.wfa[st] = *(const bf16x8*)(wa_b + lo + 16 * st); w.wfi[st] = *(const bf16x8*)(wi_b + lo + 16 * st); }
; template <int DIR>
; __device__ __forceinline__ void scan_dir(PP p, const bf16_t* xs, const ScanW& w, ScanW& wn, int ndir, int nct, bool do_next, int n, int ct, int l31, int hl, int id, int rowbase, bool latent, float (&hf)[2][16]) {
;     ...
;         for (int i = 0; i < 16; ++i) {
;             const int token = 32 * rt + 8 * (i >> 2) + 4 * hl + (i & 3);
;             const float xv = bf2f(xs[token * XS + ch]);
;             const float rr = fast_sigmoid(ga[i] + ba), ii = fast_sigmoid(gi[i] + bi);
;             const float la2 = rr * sp8l2;
;             const float av = __builtin_amdgcn_exp2f(la2);
;             const float t2 = la2 * 1.3862943611f;
;             float em1p = t2 * (1.0f + t2 * (0.5f + t2 * (0.16666667f + t2 * (0.041666668f + t2 * 0.0083333333f)))), em1e = __builtin_fmaf(av, av, -1.0f);
;             asm volatile("" : "+v"(em1p), "+v"(em1e));
;             const float em1 = (t2 > -0.1f) ? em1p : em1e;
;             a[rt][i] = av; u[rt][i] = __builtin_amdgcn_sqrtf(-em1) * (ii * xv);
;         }
;     }
;     float Ao[8], Ho[8], Ap[8], Hp[8];
; #pragma unroll
;     for (int k = 0; k < 8; ++k) {
;         const int rt = k >> 2, g = k & 3;
;         float H = 0.f, A = 1.f;
; #pragma unroll
;         for (int jj = 0; jj < 4; ++jj) { const int j = DIR ? 3 - jj : jj; const float av = a[rt][4 * g + j]; H = av * H + u[rt][4 * g + j]; A *= av; }
;         Ao[k] = A; Ho[k] = H; Ap[k] = __shfl_xor(A, 32); Hp[k] = __shfl_xor(H, 32);
;     }
	v_lshlrev_b32_e32 v9, 16, v105
	v_mul_f32_e32 v9, v12, v9
	v_add_f32_e32 v10, v192, v32
	v_mul_f32_e32 v223, v11, v9
	v_add_f32_e32 v11, v191, v48
	v_mul_f32_e32 v11, 0xbfb8aa3b, v11
	v_exp_f32_e32 v11, v11
	v_mul_f32_e32 v10, 0xbfb8aa3b, v10
	v_exp_f32_e32 v10, v10
	v_add_f32_e32 v11, 1.0, v11
	v_rcp_f32_e32 v11, v11
	v_add_f32_e32 v10, 1.0, v10
	v_rcp_f32_e32 v10, v10
	s_waitcnt lgkmcnt(0)
	v_lshlrev_b32_e32 v9, 16, v106
	v_mul_f32_e32 v9, v11, v9
	v_add_f32_e32 v11, v192, v33
	v_mul_f32_e32 v11, 0xbfb8aa3b, v11
	v_exp_f32_e32 v11, v11
	v_mul_f32_e32 v10, v194, v10
	v_exp_f32_e32 v219, v10
	v_mul_f32_e32 v10, 0x3fb17218, v10
	v_fmamk_f32 v12, v10, 0x3c088888, v186
	v_fmaak_f32 v12, v10, v12, 0x3e2aaaab
	v_add_f32_e32 v11, 1.0, v11
	v_fma_f32 v12, v10, v12, 0.5
	v_rcp_f32_e32 v11, v11
	v_fma_f32 v12, v10, v12, 1.0
	v_mul_f32_e32 v12, v10, v12
	v_fma_f32 v13, v219, v219, -1.0
	v_cmp_lt_f32_e32 vcc, s76, v10
	v_mul_f32_e32 v11, v194, v11
	v_exp_f32_e32 v225, v11
	v_cndmask_b32_e32 v10, v13, v12, vcc
	v_add_f32_e32 v12, v191, v49
	v_mul_f32_e32 v12, 0xbfb8aa3b, v12
	v_mul_f32_e32 v11, 0x3fb17218, v11
	v_exp_f32_e32 v12, v12
	v_fmamk_f32 v13, v11, 0x3c088888, v186
	v_fmaak_f32 v13, v11, v13, 0x3e2aaaab
	v_fma_f32 v13, v11, v13, 0.5
	ds_read_u16 v0, v0 offset:61360
	v_fma_f32 v13, v11, v13, 1.0
	v_add_f32_e32 v12, 1.0, v12
	v_mul_f32_e32 v13, v11, v13
	v_fma_f32 v14, v225, v225, -1.0
	v_cmp_lt_f32_e32 vcc, s76, v11
	v_sqrt_f32_e64 v10, -v10
	v_rcp_f32_e32 v12, v12
	s_waitcnt lgkmcnt(0)
	v_lshlrev_b32_e32 v0, 16, v0
	v_cndmask_b32_e32 v11, v14, v13, vcc
	v_sqrt_f32_e64 v11, -v11
	v_mul_f32_e32 v229, v10, v9
	v_mul_f32_e32 v0, v12, v0
	v_and_b32_e32 v9, 64, v188
	v_mul_f32_e32 v228, v11, v0
	v_xor_b32_e32 v0, 32, v188
	v_add_u32_e32 v9, 64, v9
	v_cmp_lt_i32_e32 vcc, v0, v9
	v_fma_f32 v9, 0, v50, v2
	v_fma_f32 v9, v52, v9, v3
	v_fma_f32 v9, v51, v9, v4
	v_fma_f32 v34, v54, v9, v5
	v_fma_f32 v9, 0, v53, v6
	v_fma_f32 v9, v55, v9, v7
	v_fma_f32 v9, v67, v9, v8
	v_fma_f32 v255, v69, v9, v76
	v_fma_f32 v9, 0, v68, v74
	v_fma_f32 v9, v71, v9, v73
	v_mul_f32_e32 v10, v50, v52
	v_fma_f32 v9, v70, v9, v209
	v_mul_f32_e32 v10, v51, v10
	v_fma_f32 v251, v75, v9, v217
	v_fma_f32 v9, 0, v72, v197
	v_mul_f32_e32 v35, v54, v10
	v_mul_f32_e32 v10, v53, v55
	v_fma_f32 v9, v78, v9, v199
	v_mul_f32_e32 v10, v67, v10
	v_fma_f32 v9, v77, v9, v204
	v_mul_f32_e32 v154, v69, v10
	v_mul_f32_e32 v10, v68, v71
	v_fma_f32 v247, v79, v9, v202
	v_fma_f32 v9, 0, v80, v196
	v_mul_f32_e32 v10, v70, v10
	v_fma_f32 v9, v146, v9, v195
	v_mul_f32_e32 v253, v75, v10
	v_mul_f32_e32 v10, v72, v78
	v_fma_f32 v9, v81, v9, v214
	v_mul_f32_e32 v10, v77, v10
	v_fma_f32 v243, v198, v9, v211
	v_fma_f32 v9, 0, v147, v206
	v_mul_f32_e32 v249, v79, v10
	v_mul_f32_e32 v10, v80, v146
	v_fma_f32 v9, v201, v9, v205
	v_mul_f32_e32 v10, v81, v10
	v_fma_f32 v9, v200, v9, v222
	v_mul_f32_e32 v245, v198, v10
	v_mul_f32_e32 v10, v147, v201
	v_fma_f32 v239, v207, v9, v221
	v_fma_f32 v9, 0, v203, v216
	v_mul_f32_e32 v10, v200, v10
	v_fma_f32 v9, v210, v9, v215
	v_mul_f32_e32 v241, v207, v10
	v_mul_f32_e32 v10, v203, v210
	v_fma_f32 v9, v208, v9, v227
	v_mul_f32_e32 v10, v208, v10
	v_fma_f32 v234, v218, v9, v226
	v_fma_f32 v9, 0, v213, v224
	v_mul_f32_e32 v236, v218, v10
	v_fma_f32 v9, v220, v9, v223
	v_mul_f32_e32 v10, v213, v220
	v_cndmask_b32_e32 v0, v188, v0, vcc
	v_fma_f32 v9, v219, v9, v229
	v_mul_f32_e32 v10, v219, v10
	v_lshlrev_b32_e32 v0, 2, v0
	v_fma_f32 v230, v225, v9, v228
	v_mul_f32_e32 v231, v225, v10
	ds_bpermute_b32 v36, v0, v35
	ds_bpermute_b32 v37, v0, v34
	ds_bpermute_b32 v155, v0, v154
	ds_bpermute_b32 v212, v0, v255
	ds_bpermute_b32 v254, v0, v253
	ds_bpermute_b32 v252, v0, v251
	ds_bpermute_b32 v250, v0, v249
	ds_bpermute_b32 v248, v0, v247
	ds_bpermute_b32 v246, v0, v245
	ds_bpermute_b32 v244, v0, v243
	ds_bpermute_b32 v242, v0, v241
	ds_bpermute_b32 v240, v0, v239
	ds_bpermute_b32 v237, v0, v236
	ds_bpermute_b32 v235, v0, v234
	ds_bpermute_b32 v232, v0, v231
	ds_bpermute_b32 v233, v0, v230
	v_cndmask_b32_e64 v0, 0, 1, s[22:23]
	v_cmp_ne_u32_e64 s[4:5], 1, v0
	s_andn2_b64 vcc, exec, s[22:23]
	s_cbranch_vccnz .LBB0_380
	v_or_b32_e32 v9, s48, v148
	s_load_dwordx2 s[48:49], s[8:9], 0x58
	s_load_dwordx2 s[82:83], s[8:9], 0x68
	v_add_u32_e32 v0, s50, v9
	v_lshlrev_b64 v[10:11], 2, v[0:1]
	v_lshl_or_b32 v0, v9, 6, v149
	s_waitcnt lgkmcnt(0)
	v_lshl_add_u64 v[12:13], s[48:49], 0, v[10:11]
	global_load_dword v189, v[12:13], off
	v_lshl_add_u64 v[12:13], s[82:83], 0, v[10:11]
	global_load_dword v190, v[12:13], off
	v_lshl_add_u64 v[10:11], s[12:13], 0, v[10:11]
	v_lshlrev_b64 v[12:13], 1, v[0:1]
	v_lshl_add_u64 v[14:15], s[20:21], 0, v[12:13]
	v_lshl_add_u64 v[12:13], s[16:17], 0, v[12:13]
	global_load_dword v144, v[10:11], off
	global_load_dwordx4 v[82:85], v[14:15], off
	global_load_dwordx4 v[86:89], v[14:15], off offset:32
	global_load_dwordx4 v[90:93], v[14:15], off offset:64
	global_load_dwordx4 v[94:97], v[12:13], off offset:32
	global_load_dwordx4 v[102:105], v[12:13], off offset:64
	global_load_dwordx4 v[98:101], v[12:13], off
	global_load_dwordx4 v[106:109], v[14:15], off offset:96
	global_load_dwordx4 v[110:113], v[12:13], off offset:96

; __device__ __forceinline__ float bf2f(bf16_t b) { return __uint_as_float(((unsigned)b) << 16); }
; __device__ __forceinline__ float fast_sigmoid(float x) { return __builtin_amdgcn_rcpf(1.0f + __builtin_amdgcn_exp2f(-1.4426950408889634f * x)); }
; template <int DIR>
; __device__ __forceinline__ void scan_dir(PP p, const bf16_t* xs, const ScanW& w, ScanW& wn, int ndir, int nct, bool do_next, int n, int ct, int l31, int hl, int id, int rowbase, bool latent, float (&hf)[2][16]) {
;     ...
;     for (int rt = 0; rt < 2; ++rt) {
;         bf16x8 af[4];
; #pragma unroll
;         for (int st = 0; st < 4; ++st) af[st] = *(const bf16x8*)(xs + (32 * rt + l31) * XS + 64 * n + 16 * st + 8 * hl);
;         f32x16 ga, gi;
; #pragma unroll
;         for (int i = 0; i < 16; ++i) { ga[i] = 0.f; gi[i] = 0.f; }
; #pragma unroll
;         for (int st = 0; st < 4; ++st) { ga = __builtin_amdgcn_mfma_f32_32x32x16_bf16(af[st], wfa[st], ga, 0, 0, 0); gi = __builtin_amdgcn_mfma_f32_32x32x16_bf16(af[st], wfi[st], gi, 0, 0, 0); }
; #pragma unroll
;         for (int i = 0; i < 16; ++i) {
;             const int token = 32 * rt + 8 * (i >> 2) + 4 * hl + (i & 3);
;             const float xv = bf2f(xs[token * XS + ch]);
;             const float rr = fast_sigmoid(ga[i] + ba), ii = fast_sigmoid(gi[i] + bi);
;             const float la2 = rr * sp8l2;
;             const float av = __builtin_amdgcn_exp2f(la2);
;             const float t2 = la2 * 1.3862943611f;
;             float em1p = t2 * (1.0f + t2 * (0.5f + t2 * (0.16666667f + t2 * (0.041666668f + t2 * 0.0083333333f)))), em1e = __builtin_fmaf(av, av, -1.0f);
;             asm volatile("" : "+v"(em1p), "+v"(em1e));
;             const float em1 = (t2 > -0.1f) ? em1p : em1e;
;             a[rt][i] = av; u[rt][i] = __builtin_amdgcn_sqrtf(-em1) * (ii * xv);
;         }
.LBB0_445:
	ds_read_b128 v[34:37], v187
	v_lshl_or_b32 v146, s80, 5, v150
	v_lshl_add_u32 v74, v146, 1, 0
	v_add_u32_e32 v0, v74, v151
	ds_read_u16 v75, v0
	ds_read_b128 v[66:69], v187 offset:32
	ds_read_b128 v[70:73], v187 offset:64
	v_add_u32_e32 v213, v74, v152
	s_and_b64 s[4:5], s[22:23], s[44:45]
	s_waitcnt vmcnt(7) lgkmcnt(3)
	s_cmp_lg_u64 s[22:23], 0
	s_cbranch_scc0 .Lscan_nomul
	v_mul_f32_e32 v193, 0x3fb8aa3b, v144
.Lscan_nomul:
	v_mfma_f32_32x32x16_bf16 v[50:65], v[34:37], v[82:85], 0
	s_waitcnt vmcnt(2)
	v_mfma_f32_32x32x16_bf16 v[34:49], v[34:37], v[98:101], 0
	s_waitcnt lgkmcnt(1)
	v_mfma_f32_32x32x16_bf16 v[50:65], v[66:69], v[86:89], v[50:65]
	v_mfma_f32_32x32x16_bf16 v[34:49], v[66:69], v[94:97], v[34:49]
	ds_read_b128 v[66:69], v187 offset:96
	s_waitcnt lgkmcnt(1)
	v_mfma_f32_32x32x16_bf16 v[50:65], v[70:73], v[90:93], v[50:65]
	v_mfma_f32_32x32x16_bf16 v[34:49], v[70:73], v[102:105], v[34:49]
	s_waitcnt vmcnt(1) lgkmcnt(0)
	v_add_u32_e32 v145, v74, v185
	ds_read_u16 v114, v145
	ds_read_u16 v115, v145 offset:1040
	ds_read_u16 v116, v145 offset:2080
	ds_read_u16 v117, v213
	ds_read_u16 v118, v213 offset:1040
	ds_read_u16 v119, v213 offset:2080
	ds_read_u16 v120, v213 offset:3120
	ds_read_u16 v121, v213 offset:8320
	ds_read_u16 v122, v213 offset:9360
	ds_read_u16 v123, v213 offset:10400
	ds_read_u16 v124, v213 offset:24960
	ds_read_u16 v125, v213 offset:26000
	ds_read_u16 v126, v213 offset:27040
	ds_read_u16 v127, v213 offset:28080
	ds_read_u16 v128, v0 offset:41600
	ds_read_u16 v129, v0 offset:42640
	ds_read_u16 v130, v0 offset:43680
	ds_read_u16 v131, v0 offset:44720
	ds_read_u16 v132, v0 offset:49920
	ds_read_u16 v133, v0 offset:50960
	ds_read_u16 v134, v0 offset:52000
	ds_read_u16 v135, v0 offset:53040
	ds_read_u16 v136, v0 offset:58240
	ds_read_u16 v137, v0 offset:59280
	ds_read_u16 v138, v0 offset:60320
	v_mfma_f32_32x32x16_bf16 v[50:65], v[66:69], v[106:109], v[50:65]
	s_waitcnt vmcnt(0)
	v_mfma_f32_32x32x16_bf16 v[34:49], v[66:69], v[110:113], v[34:49]
	s_nop 9
	v_add_f32_e32 v50, v189, v50
	v_mul_f32_e32 v50, 0xbfb8aa3b, v50
	v_exp_f32_e32 v50, v50
	v_add_f32_e32 v51, v189, v51
	v_mul_f32_e32 v51, 0xbfb8aa3b, v51
	v_exp_f32_e32 v51, v51
	v_add_f32_e32 v50, 1.0, v50
	v_add_f32_e32 v34, v190, v34
	v_mul_f32_e32 v34, 0xbfb8aa3b, v34
	v_exp_f32_e32 v34, v34
	v_rcp_f32_e32 v50, v50
	v_add_f32_e32 v35, v190, v35
	v_mul_f32_e32 v35, 0xbfb8aa3b, v35
	v_add_f32_e32 v34, 1.0, v34
	v_mul_f32_e32 v50, v193, v50
	v_rcp_f32_e32 v67, v34
	v_exp_f32_e32 v34, v50
	v_mul_f32_e32 v50, 0x3fb17218, v50
	v_fmamk_f32 v68, v50, 0x3c088888, v186
	v_fmaak_f32 v68, v50, v68, 0x3e2aaaab
	v_exp_f32_e32 v35, v35
	v_add_f32_e32 v51, 1.0, v51
	v_fma_f32 v68, v50, v68, 0.5
	v_rcp_f32_e32 v51, v51
	v_fma_f32 v68, v50, v68, 1.0
	v_mul_f32_e32 v68, v50, v68
	v_fma_f32 v69, v34, v34, -1.0
	v_cmp_lt_f32_e32 vcc, s76, v50
	v_add_f32_e32 v35, 1.0, v35
	v_lshlrev_b32_e32 v66, 16, v75
	v_cndmask_b32_e32 v50, v69, v68, vcc
	v_rcp_f32_e32 v69, v35
	v_mul_f32_e32 v35, v193, v51
	v_exp_f32_e32 v147, v35
	v_mul_f32_e32 v35, 0x3fb17218, v35
	v_fmamk_f32 v51, v35, 0x3c088888, v186
	v_fmaak_f32 v51, v35, v51, 0x3e2aaaab
	v_mul_f32_e32 v66, v67, v66
	v_add_u32_e32 v67, v74, v185
	v_fma_f32 v51, v35, v51, 0.5
	v_fma_f32 v51, v35, v51, 1.0
	v_sqrt_f32_e64 v50, -v50
	v_mul_f32_e32 v51, v35, v51
	v_fma_f32 v70, v147, v147, -1.0
	v_cmp_lt_f32_e32 vcc, s76, v35
	v_add_f32_e32 v36, v190, v36
	v_mul_f32_e32 v36, 0xbfb8aa3b, v36
	v_cndmask_b32_e32 v35, v70, v51, vcc
	v_sqrt_f32_e64 v51, -v35
	v_exp_f32_e32 v36, v36
	v_mul_f32_e32 v35, v66, v50
	s_waitcnt lgkmcnt(0)
	v_lshlrev_b32_e32 v50, 16, v114
	v_mul_f32_e32 v50, v69, v50
	v_mul_f32_e32 v195, v50, v51
	v_add_f32_e32 v36, 1.0, v36
	v_rcp_f32_e32 v36, v36
	v_add_f32_e32 v51, v189, v52
	v_mul_f32_e32 v51, 0xbfb8aa3b, v51
	v_exp_f32_e32 v51, v51
	s_waitcnt lgkmcnt(0)
	v_lshlrev_b32_e32 v50, 16, v115
	v_mul_f32_e32 v36, v36, v50
	v_add_f32_e32 v50, v189, v53
	v_mul_f32_e32 v50, 0xbfb8aa3b, v50
	v_exp_f32_e32 v50, v50
	v_add_f32_e32 v51, 1.0, v51
	v_rcp_f32_e32 v51, v51
	v_add_f32_e32 v37, v190, v37
	v_add_f32_e32 v50, 1.0, v50
	v_rcp_f32_e32 v50, v50
	v_mul_f32_e32 v51, v193, v51
	v_exp_f32_e32 v196, v51
	v_mul_f32_e32 v51, 0x3fb17218, v51
	v_fmamk_f32 v52, v51, 0x3c088888, v186
	v_fmaak_f32 v52, v51, v52, 0x3e2aaaab
	v_mul_f32_e32 v50, v193, v50
	v_fma_f32 v52, v51, v52, 0.5
	v_mul_f32_e32 v37, 0xbfb8aa3b, v37
	v_exp_f32_e32 v198, v50
	v_mul_f32_e32 v50, 0x3fb17218, v50
	v_fma_f32 v52, v51, v52, 1.0
	v_exp_f32_e32 v37, v37
	v_fmamk_f32 v53, v50, 0x3c088888, v186
	v_mul_f32_e32 v52, v51, v52
	v_fma_f32 v66, v196, v196, -1.0
	v_fmaak_f32 v53, v50, v53, 0x3e2aaaab
	v_cmp_lt_f32_e32 vcc, s76, v51
	v_fma_f32 v53, v50, v53, 0.5
	v_fma_f32 v53, v50, v53, 1.0
	v_cndmask_b32_e32 v51, v66, v52, vcc
	v_sqrt_f32_e64 v51, -v51
	v_add_f32_e32 v37, 1.0, v37
	v_mul_f32_e32 v53, v50, v53
	v_fma_f32 v66, v198, v198, -1.0
	v_cmp_lt_f32_e32 vcc, s76, v50
	v_rcp_f32_e32 v37, v37
	v_mul_f32_e32 v197, v36, v51
	v_cndmask_b32_e32 v50, v66, v53, vcc
	v_sqrt_f32_e64 v50, -v50
	s_waitcnt lgkmcnt(0)
	v_lshlrev_b32_e32 v36, 16, v116
	v_mul_f32_e32 v36, v37, v36
	v_add_f32_e32 v38, v190, v38
	v_mul_f32_e32 v199, v50, v36
	v_mul_f32_e32 v38, 0xbfb8aa3b, v38
	v_exp_f32_e32 v38, v38
	v_add_f32_e32 v37, v189, v54
	v_mul_f32_e32 v37, 0xbfb8aa3b, v37
	v_exp_f32_e32 v37, v37
	s_waitcnt lgkmcnt(0)
; __device__ __forceinline__ float bf2f(bf16_t b) { return __uint_as_float(((unsigned)b) << 16); }
; __device__ __forceinline__ float fast_sigmoid(float x) { return __builtin_amdgcn_rcpf(1.0f + __builtin_amdgcn_exp2f(-1.4426950408889634f * x)); }
; template <int DIR>
; __device__ __forceinline__ void scan_dir(PP p, const bf16_t* xs, const ScanW& w, ScanW& wn, int ndir, int nct, bool do_next, int n, int ct, int l31, int hl, int id, int rowbase, bool latent, float (&hf)[2][16]) {
;     ...
;         for (int i = 0; i < 16; ++i) {
;             const int token = 32 * rt + 8 * (i >> 2) + 4 * hl + (i & 3);
;             const float xv = bf2f(xs[token * XS + ch]);
;             const float rr = fast_sigmoid(ga[i] + ba), ii = fast_sigmoid(gi[i] + bi);
;             const float la2 = rr * sp8l2;
;             const float av = __builtin_amdgcn_exp2f(la2);
;             const float t2 = la2 * 1.3862943611f;
;             float em1p = t2 * (1.0f + t2 * (0.5f + t2 * (0.16666667f + t2 * (0.041666668f + t2 * 0.0083333333f)))), em1e = __builtin_fmaf(av, av, -1.0f);
;             asm volatile("" : "+v"(em1p), "+v"(em1e));
;             const float em1 = (t2 > -0.1f) ? em1p : em1e;
;             a[rt][i] = av; u[rt][i] = __builtin_amdgcn_sqrtf(-em1) * (ii * xv);
;         }
	v_lshlrev_b32_e32 v50, 16, v117
	v_add_f32_e32 v36, 1.0, v38
	v_rcp_f32_e32 v38, v36
	v_add_f32_e32 v37, 1.0, v37
	v_rcp_f32_e32 v37, v37
	v_add_f32_e32 v39, v190, v39
	v_mul_f32_e32 v50, v38, v50
	v_add_f32_e32 v38, v189, v55
	v_mul_f32_e32 v38, 0xbfb8aa3b, v38
	v_exp_f32_e32 v38, v38
	v_mul_f32_e32 v37, v193, v37
	v_exp_f32_e32 v36, v37
	v_mul_f32_e32 v37, 0x3fb17218, v37
	v_fmamk_f32 v51, v37, 0x3c088888, v186
	v_fmaak_f32 v51, v37, v51, 0x3e2aaaab
	v_add_f32_e32 v38, 1.0, v38
	v_fma_f32 v51, v37, v51, 0.5
	v_rcp_f32_e32 v38, v38
	v_fma_f32 v51, v37, v51, 1.0
	v_mul_f32_e32 v39, 0xbfb8aa3b, v39
	v_mul_f32_e32 v51, v37, v51
	v_fma_f32 v52, v36, v36, -1.0
	v_exp_f32_e32 v39, v39
	v_cmp_lt_f32_e32 vcc, s76, v37
	v_add_f32_e32 v40, v190, v40
	v_add_f32_e32 v39, 1.0, v39
	v_cndmask_b32_e32 v37, v52, v51, vcc
	v_mul_f32_e32 v52, v193, v38
	v_exp_f32_e32 v38, v52
	v_mul_f32_e32 v52, 0x3fb17218, v52
	v_sqrt_f32_e64 v37, -v37
	v_fmamk_f32 v53, v52, 0x3c088888, v186
	v_rcp_f32_e32 v39, v39
	v_fmaak_f32 v53, v52, v53, 0x3e2aaaab
	v_mul_f32_e32 v40, 0xbfb8aa3b, v40
	v_fma_f32 v53, v52, v53, 0.5
	v_exp_f32_e32 v40, v40
	v_fma_f32 v53, v52, v53, 1.0
	v_mul_f32_e32 v53, v52, v53
	v_fma_f32 v54, v38, v38, -1.0
	v_mul_f32_e32 v37, v37, v50
	s_waitcnt lgkmcnt(0)
	v_lshlrev_b32_e32 v50, 16, v118
	v_mul_f32_e32 v39, v39, v50
	v_add_f32_e32 v51, v189, v56
	v_mul_f32_e32 v51, 0xbfb8aa3b, v51
	v_add_f32_e32 v40, 1.0, v40
	v_exp_f32_e32 v51, v51
	v_rcp_f32_e32 v40, v40
	s_waitcnt lgkmcnt(0)
	v_lshlrev_b32_e32 v50, 16, v119
	v_cmp_lt_f32_e32 vcc, s76, v52
	v_add_f32_e32 v51, 1.0, v51
	v_mul_f32_e32 v40, v40, v50
	v_add_f32_e32 v50, v189, v57
	v_rcp_f32_e32 v51, v51
	v_mul_f32_e32 v50, 0xbfb8aa3b, v50
	v_cndmask_b32_e32 v52, v54, v53, vcc
	v_exp_f32_e32 v50, v50
	v_sqrt_f32_e64 v52, -v52
	v_mul_f32_e32 v51, v193, v51
	v_exp_f32_e32 v200, v51
	v_mul_f32_e32 v51, 0x3fb17218, v51
	v_add_f32_e32 v50, 1.0, v50
	v_mul_f32_e32 v39, v52, v39
	v_fmamk_f32 v52, v51, 0x3c088888, v186
	v_rcp_f32_e32 v50, v50
	v_fmaak_f32 v52, v51, v52, 0x3e2aaaab
	v_add_f32_e32 v41, v190, v41
	v_fma_f32 v52, v51, v52, 0.5
	v_mul_f32_e32 v41, 0xbfb8aa3b, v41
	v_fma_f32 v52, v51, v52, 1.0
	v_exp_f32_e32 v41, v41
	v_mul_f32_e32 v52, v51, v52
	v_fma_f32 v53, v200, v200, -1.0
	v_mul_f32_e32 v50, v193, v50
	v_cmp_lt_f32_e32 vcc, s76, v51
	v_exp_f32_e32 v202, v50
	v_mul_f32_e32 v50, 0x3fb17218, v50
	v_cndmask_b32_e32 v51, v53, v52, vcc
	v_fmamk_f32 v53, v50, 0x3c088888, v186
	v_sqrt_f32_e64 v51, -v51
	v_add_f32_e32 v41, 1.0, v41
	v_fmaak_f32 v53, v50, v53, 0x3e2aaaab
	v_rcp_f32_e32 v41, v41
	v_fma_f32 v53, v50, v53, 0.5
	v_fma_f32 v53, v50, v53, 1.0
	v_mul_f32_e32 v53, v50, v53
	v_fma_f32 v54, v202, v202, -1.0
	v_cmp_lt_f32_e32 vcc, s76, v50
	v_mul_f32_e32 v201, v51, v40
	s_waitcnt lgkmcnt(0)
	v_lshlrev_b32_e32 v40, 16, v120
	v_cndmask_b32_e32 v50, v54, v53, vcc
	v_sqrt_f32_e64 v50, -v50
	v_mul_f32_e32 v40, v41, v40
	v_add_f32_e32 v41, v189, v58
	v_mul_f32_e32 v41, 0xbfb8aa3b, v41
	v_exp_f32_e32 v41, v41
	v_add_f32_e32 v42, v190, v42
	v_mul_f32_e32 v203, v50, v40
	v_mul_f32_e32 v42, 0xbfb8aa3b, v42
	v_exp_f32_e32 v42, v42
	v_add_f32_e32 v41, 1.0, v41
	v_rcp_f32_e32 v41, v41
	s_waitcnt lgkmcnt(0)
	v_lshlrev_b32_e32 v50, 16, v121
	v_add_f32_e32 v40, 1.0, v42
	v_rcp_f32_e32 v42, v40
	v_mul_f32_e32 v41, v193, v41
	v_exp_f32_e32 v40, v41
	v_mul_f32_e32 v41, 0x3fb17218, v41
	v_fmamk_f32 v51, v41, 0x3c088888, v186
	v_fmaak_f32 v51, v41, v51, 0x3e2aaaab
	v_mul_f32_e32 v50, v42, v50
	v_add_f32_e32 v42, v189, v59
	v_fma_f32 v51, v41, v51, 0.5
	v_mul_f32_e32 v42, 0xbfb8aa3b, v42
	v_fma_f32 v51, v41, v51, 1.0
	v_exp_f32_e32 v42, v42
	v_mul_f32_e32 v51, v41, v51
	v_fma_f32 v52, v40, v40, -1.0
	v_cmp_lt_f32_e32 vcc, s76, v41
	v_add_f32_e32 v42, 1.0, v42
	v_rcp_f32_e32 v42, v42
	v_cndmask_b32_e32 v41, v52, v51, vcc
	v_sqrt_f32_e64 v41, -v41
	v_add_f32_e32 v43, v190, v43
	v_mul_f32_e32 v52, v193, v42
	v_mul_f32_e32 v43, 0xbfb8aa3b, v43
	v_mul_f32_e32 v41, v41, v50
	s_waitcnt lgkmcnt(0)
	v_lshlrev_b32_e32 v50, 16, v122
	v_add_f32_e32 v51, v189, v60
	v_mul_f32_e32 v51, 0xbfb8aa3b, v51
	v_exp_f32_e32 v42, v52
	v_mul_f32_e32 v52, 0x3fb17218, v52
	v_exp_f32_e32 v51, v51
	v_exp_f32_e32 v43, v43
	v_fmamk_f32 v53, v52, 0x3c088888, v186
	v_fmaak_f32 v53, v52, v53, 0x3e2aaaab
	v_fma_f32 v53, v52, v53, 0.5
	v_fma_f32 v53, v52, v53, 1.0
	v_add_f32_e32 v51, 1.0, v51
	v_add_f32_e32 v43, 1.0, v43
	v_mul_f32_e32 v53, v52, v53
	v_fma_f32 v54, v42, v42, -1.0
	v_cmp_lt_f32_e32 vcc, s76, v52
	v_rcp_f32_e32 v51, v51
	v_rcp_f32_e32 v43, v43
	v_add_f32_e32 v44, v190, v44
	v_cndmask_b32_e32 v52, v54, v53, vcc
	v_sqrt_f32_e64 v52, -v52
	v_mul_f32_e32 v51, v193, v51
	v_mul_f32_e32 v43, v43, v50
	v_exp_f32_e32 v204, v51
	v_mul_f32_e32 v51, 0x3fb17218, v51
	v_mul_f32_e32 v43, v52, v43
	v_fmamk_f32 v52, v51, 0x3c088888, v186
	v_fmaak_f32 v52, v51, v52, 0x3e2aaaab
	v_mul_f32_e32 v44, 0xbfb8aa3b, v44
	v_fma_f32 v52, v51, v52, 0.5
	v_exp_f32_e32 v44, v44
	v_fma_f32 v52, v51, v52, 1.0
	v_mul_f32_e32 v52, v51, v52
	v_fma_f32 v53, v204, v204, -1.0
	v_cmp_lt_f32_e32 vcc, s76, v51
	v_add_f32_e32 v44, 1.0, v44
	v_rcp_f32_e32 v44, v44
	v_cndmask_b32_e32 v51, v53, v52, vcc
	v_add_f32_e32 v52, v189, v61
	v_mul_f32_e32 v52, 0xbfb8aa3b, v52
	v_exp_f32_e32 v52, v52
	s_waitcnt lgkmcnt(0)
; __device__ __forceinline__ float bf2f(bf16_t b) { return __uint_as_float(((unsigned)b) << 16); }
; __device__ __forceinline__ float fast_sigmoid(float x) { return __builtin_amdgcn_rcpf(1.0f + __builtin_amdgcn_exp2f(-1.4426950408889634f * x)); }
; template <int DIR>
; __device__ __forceinline__ void scan_dir(PP p, const bf16_t* xs, const ScanW& w, ScanW& wn, int ndir, int nct, bool do_next, int n, int ct, int l31, int hl, int id, int rowbase, bool latent, float (&hf)[2][16]) {
;     ...
;     for (int rt = 0; rt < 2; ++rt) {
;         bf16x8 af[4];
; #pragma unroll
;         for (int st = 0; st < 4; ++st) af[st] = *(const bf16x8*)(xs + (32 * rt + l31) * XS + 64 * n + 16 * st + 8 * hl);
;         f32x16 ga, gi;
; #pragma unroll
;         for (int i = 0; i < 16; ++i) { ga[i] = 0.f; gi[i] = 0.f; }
; #pragma unroll
;         for (int st = 0; st < 4; ++st) { ga = __builtin_amdgcn_mfma_f32_32x32x16_bf16(af[st], wfa[st], ga, 0, 0, 0); gi = __builtin_amdgcn_mfma_f32_32x32x16_bf16(af[st], wfi[st], gi, 0, 0, 0); }
; #pragma unroll
;         for (int i = 0; i < 16; ++i) {
;             const int token = 32 * rt + 8 * (i >> 2) + 4 * hl + (i & 3);
;             const float xv = bf2f(xs[token * XS + ch]);
;             const float rr = fast_sigmoid(ga[i] + ba), ii = fast_sigmoid(gi[i] + bi);
;             const float la2 = rr * sp8l2;
;             const float av = __builtin_amdgcn_exp2f(la2);
;             const float t2 = la2 * 1.3862943611f;
;             float em1p = t2 * (1.0f + t2 * (0.5f + t2 * (0.16666667f + t2 * (0.041666668f + t2 * 0.0083333333f)))), em1e = __builtin_fmaf(av, av, -1.0f);
;             asm volatile("" : "+v"(em1p), "+v"(em1e));
;             const float em1 = (t2 > -0.1f) ? em1p : em1e;
;             a[rt][i] = av; u[rt][i] = __builtin_amdgcn_sqrtf(-em1) * (ii * xv);
;         }
	v_lshlrev_b32_e32 v50, 16, v123
	v_mul_f32_e32 v50, v44, v50
	v_add_f32_e32 v45, v190, v45
	v_add_f32_e32 v44, 1.0, v52
	v_rcp_f32_e32 v44, v44
	v_mul_f32_e32 v45, 0xbfb8aa3b, v45
	v_exp_f32_e32 v52, v45
	v_add_f32_e32 v45, v189, v62
	v_mul_f32_e32 v44, v193, v44
	v_mul_f32_e32 v54, 0x3fb17218, v44
	v_mul_f32_e32 v45, 0xbfb8aa3b, v45
	v_exp_f32_e32 v205, v44
	v_fmamk_f32 v44, v54, 0x3c088888, v186
	v_exp_f32_e32 v45, v45
	v_fmaak_f32 v44, v54, v44, 0x3e2aaaab
	v_fma_f32 v44, v54, v44, 0.5
	v_fma_f32 v44, v54, v44, 1.0
	v_mul_f32_e32 v55, v54, v44
	v_add_f32_e32 v44, 1.0, v45
	v_rcp_f32_e32 v44, v44
	v_add_f32_e32 v57, v189, v63
	v_mul_f32_e32 v57, 0xbfb8aa3b, v57
	v_exp_f32_e32 v57, v57
	v_mul_f32_e32 v45, v193, v44
	v_mul_f32_e32 v154, 0x3fb17218, v45
	v_exp_f32_e32 v44, v45
	v_fmamk_f32 v45, v154, 0x3c088888, v186
	v_fmaak_f32 v45, v154, v45, 0x3e2aaaab
	v_fma_f32 v45, v154, v45, 0.5
	v_fma_f32 v45, v154, v45, 1.0
	v_mul_f32_e32 v155, v154, v45
	v_add_f32_e32 v45, 1.0, v57
	v_rcp_f32_e32 v45, v45
	v_add_f32_e32 v58, v189, v64
	v_mul_f32_e32 v58, 0xbfb8aa3b, v58
	v_exp_f32_e32 v58, v58
	v_mul_f32_e32 v57, v193, v45
	v_mul_f32_e32 v159, 0x3fb17218, v57
	v_exp_f32_e32 v45, v57
	v_fmamk_f32 v57, v159, 0x3c088888, v186
	v_fmaak_f32 v57, v159, v57, 0x3e2aaaab
	v_fma_f32 v57, v159, v57, 0.5
	v_fma_f32 v57, v159, v57, 1.0
	v_mul_f32_e32 v209, v159, v57
	v_add_f32_e32 v57, 1.0, v58
	v_rcp_f32_e32 v57, v57
	v_add_f32_e32 v58, v189, v65
	v_mul_f32_e32 v58, 0xbfb8aa3b, v58
	v_exp_f32_e32 v58, v58
	v_mul_f32_e32 v57, v193, v57
	v_mul_f32_e32 v222, 0x3fb17218, v57
	v_exp_f32_e32 v206, v57
	v_fmamk_f32 v57, v222, 0x3c088888, v186
	v_fmaak_f32 v57, v222, v57, 0x3e2aaaab
	v_fma_f32 v57, v222, v57, 0.5
	v_fma_f32 v57, v222, v57, 1.0
	v_mul_f32_e32 v223, v222, v57
	v_add_f32_e32 v57, 1.0, v58
	v_rcp_f32_e32 v57, v57
	v_sqrt_f32_e64 v51, -v51
	v_fma_f32 v56, v205, v205, -1.0
	v_fma_f32 v156, v44, v44, -1.0
	v_mul_f32_e32 v57, v193, v57
	v_mul_f32_e32 v226, 0x3fb17218, v57
	v_exp_f32_e32 v207, v57
	v_fmamk_f32 v57, v226, 0x3c088888, v186
	v_fmaak_f32 v57, v226, v57, 0x3e2aaaab
	v_fma_f32 v57, v226, v57, 0.5
	v_fma_f32 v57, v226, v57, 1.0
	v_fma_f32 v210, v45, v45, -1.0
	v_fma_f32 v224, v206, v206, -1.0
	v_mul_f32_e32 v227, v226, v57
	v_fma_f32 v228, v207, v207, -1.0
	ds_read_u16 v53, v213 offset:11440
	ds_read_u16 v70, v213 offset:16640
	ds_read_u16 v158, v213 offset:17680
	ds_read_u16 v212, v213 offset:18720
	ds_read_u16 v225, v213 offset:19760
	ds_read_b128 v[66:69], v187 offset:33280
	ds_read_b128 v[214:217], v187 offset:33312
	v_mul_f32_e32 v208, v51, v50
	v_add_f32_e32 v50, 1.0, v52
	v_cmp_lt_f32_e32 vcc, s76, v54
	v_rcp_f32_e32 v72, v50
	s_waitcnt lgkmcnt(6)
	v_lshlrev_b32_e32 v71, 16, v53
	v_cndmask_b32_e32 v50, v56, v55, vcc
	v_sqrt_f32_e64 v73, -v50
	v_mul_f32_e32 v71, v72, v71
	s_waitcnt lgkmcnt(1)
	v_mfma_f32_32x32x16_bf16 v[50:65], v[66:69], v[82:85], 0
	v_lshlrev_b32_e32 v230, 16, v70
	v_mul_f32_e32 v211, v73, v71
	v_add_f32_e32 v46, v190, v46
	v_mul_f32_e32 v46, 0xbfb8aa3b, v46
	v_exp_f32_e32 v46, v46
	ds_read_b128 v[218:221], v187 offset:33344
	v_cmp_lt_f32_e32 vcc, s76, v154
	v_mfma_f32_32x32x16_bf16 v[66:81], v[66:69], v[98:101], 0
	v_add_f32_e32 v46, 1.0, v46
	v_add_f32_e32 v47, v190, v47
	v_rcp_f32_e32 v46, v46
	v_cndmask_b32_e32 v154, v156, v155, vcc
	v_mul_f32_e32 v47, 0xbfb8aa3b, v47
	v_sqrt_f32_e64 v154, -v154
	v_exp_f32_e32 v155, v47
	s_waitcnt lgkmcnt(1)
	v_mfma_f32_32x32x16_bf16 v[66:81], v[214:217], v[94:97], v[66:81]
	v_mul_f32_e32 v46, v46, v230
	v_mul_f32_e32 v47, v154, v46
	v_add_f32_e32 v154, 1.0, v155
	v_rcp_f32_e32 v154, v154
	v_add_f32_e32 v48, v190, v48
	v_lshlrev_b32_e32 v46, 16, v158
	v_cmp_lt_f32_e32 vcc, s76, v159
	v_mfma_f32_32x32x16_bf16 v[50:65], v[214:217], v[86:89], v[50:65]
	ds_read_b128 v[214:217], v187 offset:33376
	v_mul_f32_e32 v48, 0xbfb8aa3b, v48
	v_cndmask_b32_e32 v155, v210, v209, vcc
	v_mul_f32_e32 v46, v154, v46
	v_exp_f32_e32 v154, v48
	v_add_f32_e32 v49, v190, v49
	v_sqrt_f32_e64 v155, -v155
	s_waitcnt lgkmcnt(1)
	v_mfma_f32_32x32x16_bf16 v[66:81], v[218:221], v[102:105], v[66:81]
	v_mul_f32_e32 v49, 0xbfb8aa3b, v49
	v_exp_f32_e32 v49, v49
	v_add_f32_e32 v154, 1.0, v154
	v_cmp_lt_f32_e32 vcc, s76, v222
	v_mul_f32_e32 v48, v155, v46
	v_rcp_f32_e32 v154, v154
	v_cndmask_b32_e32 v155, v224, v223, vcc
	v_mfma_f32_32x32x16_bf16 v[50:65], v[218:221], v[90:93], v[50:65]
	v_sqrt_f32_e64 v155, -v155
	v_add_f32_e32 v49, 1.0, v49
	v_rcp_f32_e32 v49, v49
	v_lshlrev_b32_e32 v46, 16, v212
	v_cmp_lt_f32_e32 vcc, s76, v226
	v_mul_f32_e32 v46, v154, v46
	v_mul_f32_e32 v209, v155, v46
	s_waitcnt lgkmcnt(0)
	v_mfma_f32_32x32x16_bf16 v[66:81], v[214:217], v[110:113], v[66:81]
	v_cndmask_b32_e32 v154, v228, v227, vcc
	v_sqrt_f32_e64 v154, -v154
	v_lshlrev_b32_e32 v46, 16, v225
	v_mul_f32_e32 v46, v49, v46
	v_mul_f32_e32 v210, v154, v46
	v_mul_f32_e32 v158, v205, v204
	v_mfma_f32_32x32x16_bf16 v[50:65], v[214:217], v[106:109], v[50:65]
	s_nop 3
	v_add_f32_e32 v49, v190, v66
	v_mul_f32_e32 v49, 0xbfb8aa3b, v49
	v_exp_f32_e32 v49, v49
	v_mul_f32_e32 v158, v42, v158
	v_mul_f32_e32 v217, v40, v158
	v_mul_f32_e32 v158, v207, v206
	v_add_f32_e32 v49, 1.0, v49
	s_nop 0
	v_add_f32_e32 v46, v189, v50
	v_mul_f32_e32 v46, 0xbfb8aa3b, v46
	v_exp_f32_e32 v46, v46
	v_rcp_f32_e32 v49, v49
	s_waitcnt lgkmcnt(0)
; __device__ __forceinline__ float bf2f(bf16_t b) { return __uint_as_float(((unsigned)b) << 16); }
; __device__ __forceinline__ float fast_sigmoid(float x) { return __builtin_amdgcn_rcpf(1.0f + __builtin_amdgcn_exp2f(-1.4426950408889634f * x)); }
; template <int DIR>
; __device__ __forceinline__ void scan_dir(PP p, const bf16_t* xs, const ScanW& w, ScanW& wn, int ndir, int nct, bool do_next, int n, int ct, int l31, int hl, int id, int rowbase, bool latent, float (&hf)[2][16]) {
;     ...
;         for (int i = 0; i < 16; ++i) {
;             const int token = 32 * rt + 8 * (i >> 2) + 4 * hl + (i & 3);
;             const float xv = bf2f(xs[token * XS + ch]);
;             const float rr = fast_sigmoid(ga[i] + ba), ii = fast_sigmoid(gi[i] + bi);
;             const float la2 = rr * sp8l2;
;             const float av = __builtin_amdgcn_exp2f(la2);
;             const float t2 = la2 * 1.3862943611f;
;             float em1p = t2 * (1.0f + t2 * (0.5f + t2 * (0.16666667f + t2 * (0.041666668f + t2 * 0.0083333333f)))), em1e = __builtin_fmaf(av, av, -1.0f);
;             asm volatile("" : "+v"(em1p), "+v"(em1e));
;             const float em1 = (t2 > -0.1f) ? em1p : em1e;
;             a[rt][i] = av; u[rt][i] = __builtin_amdgcn_sqrtf(-em1) * (ii * xv);
;         }
	v_lshlrev_b32_e32 v50, 16, v124
	v_add_f32_e32 v52, v189, v52
	v_add_f32_e32 v46, 1.0, v46
	v_rcp_f32_e32 v46, v46
	v_mul_f32_e32 v49, v49, v50
	v_add_f32_e32 v50, v189, v51
	v_mul_f32_e32 v50, 0xbfb8aa3b, v50
	v_exp_f32_e32 v50, v50
	v_mul_f32_e32 v66, v193, v46
	v_exp_f32_e32 v46, v66
	v_mul_f32_e32 v66, 0x3fb17218, v66
	v_fmamk_f32 v154, v66, 0x3c088888, v186
	v_fmaak_f32 v154, v66, v154, 0x3e2aaaab
	v_add_f32_e32 v50, 1.0, v50
	v_fma_f32 v154, v66, v154, 0.5
	v_add_f32_e32 v51, v190, v67
	v_rcp_f32_e32 v50, v50
	v_fma_f32 v154, v66, v154, 1.0
	v_mul_f32_e32 v51, 0xbfb8aa3b, v51
	v_mul_f32_e32 v154, v66, v154
	v_fma_f32 v155, v46, v46, -1.0
	v_exp_f32_e32 v51, v51
	v_cmp_lt_f32_e32 vcc, s76, v66
	v_add_f32_e32 v51, 1.0, v51
	v_cndmask_b32_e32 v66, v155, v154, vcc
	v_mul_f32_e32 v154, v193, v50
	v_exp_f32_e32 v50, v154
	v_mul_f32_e32 v154, 0x3fb17218, v154
	v_sqrt_f32_e64 v66, -v66
	v_fmamk_f32 v155, v154, 0x3c088888, v186
	v_rcp_f32_e32 v51, v51
	v_fmaak_f32 v155, v154, v155, 0x3e2aaaab
	v_fma_f32 v155, v154, v155, 0.5
	v_fma_f32 v155, v154, v155, 1.0
	v_mul_f32_e32 v155, v154, v155
	v_fma_f32 v156, v50, v50, -1.0
	v_mul_f32_e32 v49, v49, v66
	s_waitcnt lgkmcnt(0)
	v_lshlrev_b32_e32 v66, 16, v125
	v_mul_f32_e32 v52, 0xbfb8aa3b, v52
	v_add_f32_e32 v67, v190, v68
	v_mul_f32_e32 v51, v51, v66
	v_exp_f32_e32 v52, v52
	v_mul_f32_e32 v67, 0xbfb8aa3b, v67
	v_exp_f32_e32 v67, v67
	v_cmp_lt_f32_e32 vcc, s76, v154
	v_add_f32_e32 v52, 1.0, v52
	v_rcp_f32_e32 v52, v52
	s_waitcnt lgkmcnt(0)
	v_lshlrev_b32_e32 v68, 16, v126
	v_add_f32_e32 v66, 1.0, v67
	v_add_f32_e32 v53, v189, v53
	v_cndmask_b32_e32 v154, v156, v155, vcc
	v_rcp_f32_e32 v67, v66
	v_mul_f32_e32 v53, 0xbfb8aa3b, v53
	v_sqrt_f32_e64 v154, -v154
	v_exp_f32_e32 v53, v53
	v_mul_f32_e32 v52, v193, v52
	v_exp_f32_e32 v66, v52
	v_mul_f32_e32 v52, 0x3fb17218, v52
	v_mul_f32_e32 v67, v67, v68
	v_add_f32_e32 v68, v190, v69
	v_mul_f32_e32 v51, v51, v154
	v_fmamk_f32 v154, v52, 0x3c088888, v186
	v_mul_f32_e32 v68, 0xbfb8aa3b, v68
	v_add_f32_e32 v53, 1.0, v53
	v_fmaak_f32 v154, v52, v154, 0x3e2aaaab
	v_exp_f32_e32 v68, v68
	v_rcp_f32_e32 v53, v53
	v_fma_f32 v154, v52, v154, 0.5
	v_fma_f32 v154, v52, v154, 1.0
	v_mul_f32_e32 v154, v52, v154
	v_fma_f32 v155, v66, v66, -1.0
	v_cmp_lt_f32_e32 vcc, s76, v52
	v_add_f32_e32 v68, 1.0, v68
	v_mul_f32_e32 v53, v193, v53
	v_cndmask_b32_e32 v52, v155, v154, vcc
	v_rcp_f32_e32 v154, v68
	v_exp_f32_e32 v68, v53
	v_mul_f32_e32 v53, 0x3fb17218, v53
	v_fmamk_f32 v155, v53, 0x3c088888, v186
	v_fmaak_f32 v155, v53, v155, 0x3e2aaaab
	v_fma_f32 v155, v53, v155, 0.5
	v_fma_f32 v155, v53, v155, 1.0
	v_sqrt_f32_e64 v52, -v52
	v_mul_f32_e32 v155, v53, v155
	v_fma_f32 v156, v68, v68, -1.0
	v_cmp_lt_f32_e32 vcc, s76, v53
	v_mul_f32_e32 v67, v67, v52
	s_waitcnt lgkmcnt(0)
	v_lshlrev_b32_e32 v52, 16, v127
	v_cndmask_b32_e32 v53, v156, v155, vcc
	v_sqrt_f32_e64 v53, -v53
	v_mul_f32_e32 v52, v154, v52
	v_add_f32_e32 v56, v189, v56
	v_mul_f32_e32 v56, 0xbfb8aa3b, v56
	v_mul_f32_e32 v69, v53, v52
	v_add_f32_e32 v53, v189, v54
	v_add_f32_e32 v54, v190, v70
	v_mul_f32_e32 v54, 0xbfb8aa3b, v54
	v_exp_f32_e32 v54, v54
	v_mul_f32_e32 v53, 0xbfb8aa3b, v53
	v_exp_f32_e32 v53, v53
	s_waitcnt lgkmcnt(0)
	v_lshlrev_b32_e32 v70, 16, v128
	v_add_f32_e32 v52, 1.0, v54
	v_rcp_f32_e32 v54, v52
	v_add_f32_e32 v53, 1.0, v53
	v_rcp_f32_e32 v53, v53
	v_exp_f32_e32 v56, v56
	v_mul_f32_e32 v70, v54, v70
	v_add_f32_e32 v54, v189, v55
	v_mul_f32_e32 v54, 0xbfb8aa3b, v54
	v_exp_f32_e32 v54, v54
	v_mul_f32_e32 v53, v193, v53
	v_exp_f32_e32 v52, v53
	v_mul_f32_e32 v53, 0x3fb17218, v53
	v_fmamk_f32 v154, v53, 0x3c088888, v186
	v_fmaak_f32 v154, v53, v154, 0x3e2aaaab
	v_add_f32_e32 v54, 1.0, v54
	v_fma_f32 v154, v53, v154, 0.5
	v_add_f32_e32 v55, v190, v71
	v_rcp_f32_e32 v54, v54
	v_fma_f32 v154, v53, v154, 1.0
	v_mul_f32_e32 v55, 0xbfb8aa3b, v55
	v_mul_f32_e32 v154, v53, v154
	v_fma_f32 v155, v52, v52, -1.0
	v_exp_f32_e32 v55, v55
	v_cmp_lt_f32_e32 vcc, s76, v53
	v_add_f32_e32 v55, 1.0, v55
	v_cndmask_b32_e32 v53, v155, v154, vcc
	v_mul_f32_e32 v154, v193, v54
	v_exp_f32_e32 v54, v154
	v_mul_f32_e32 v154, 0x3fb17218, v154
	v_sqrt_f32_e64 v53, -v53
	v_fmamk_f32 v155, v154, 0x3c088888, v186
	v_rcp_f32_e32 v55, v55
	v_fmaak_f32 v155, v154, v155, 0x3e2aaaab
	v_fma_f32 v155, v154, v155, 0.5
	v_fma_f32 v155, v154, v155, 1.0
	v_mul_f32_e32 v155, v154, v155
	v_fma_f32 v156, v54, v54, -1.0
	v_mul_f32_e32 v53, v53, v70
	s_waitcnt lgkmcnt(0)
	v_lshlrev_b32_e32 v70, 16, v129
	v_add_f32_e32 v71, v190, v72
	v_mul_f32_e32 v55, v55, v70
	v_mul_f32_e32 v71, 0xbfb8aa3b, v71
	v_exp_f32_e32 v71, v71
	v_add_f32_e32 v56, 1.0, v56
	v_cmp_lt_f32_e32 vcc, s76, v154
	v_rcp_f32_e32 v56, v56
	s_waitcnt lgkmcnt(0)
	v_lshlrev_b32_e32 v72, 16, v130
	v_add_f32_e32 v70, 1.0, v71
	v_add_f32_e32 v57, v189, v57
	v_cndmask_b32_e32 v154, v156, v155, vcc
	v_rcp_f32_e32 v71, v70
	v_mul_f32_e32 v57, 0xbfb8aa3b, v57
	v_sqrt_f32_e64 v154, -v154
	v_exp_f32_e32 v57, v57
	v_mul_f32_e32 v56, v193, v56
	v_exp_f32_e32 v70, v56
	v_mul_f32_e32 v56, 0x3fb17218, v56
	v_mul_f32_e32 v71, v71, v72
	v_add_f32_e32 v72, v190, v73
	v_mul_f32_e32 v55, v154, v55
	v_fmamk_f32 v154, v56, 0x3c088888, v186
	v_mul_f32_e32 v72, 0xbfb8aa3b, v72
	v_add_f32_e32 v57, 1.0, v57
	v_fmaak_f32 v154, v56, v154, 0x3e2aaaab
	v_exp_f32_e32 v72, v72
	v_rcp_f32_e32 v57, v57
	v_fma_f32 v154, v56, v154, 0.5
	v_fma_f32 v154, v56, v154, 1.0
	v_mul_f32_e32 v154, v56, v154
	v_fma_f32 v155, v70, v70, -1.0
	v_cmp_lt_f32_e32 vcc, s76, v56
	v_add_f32_e32 v72, 1.0, v72
	v_mul_f32_e32 v57, v193, v57
	v_cndmask_b32_e32 v56, v155, v154, vcc
	v_rcp_f32_e32 v154, v72
	v_exp_f32_e32 v72, v57
	v_mul_f32_e32 v57, 0x3fb17218, v57
	v_fmamk_f32 v155, v57, 0x3c088888, v186
	v_fmaak_f32 v155, v57, v155, 0x3e2aaaab
	v_fma_f32 v155, v57, v155, 0.5
	v_fma_f32 v155, v57, v155, 1.0
	v_sqrt_f32_e64 v56, -v56
	v_mul_f32_e32 v155, v57, v155
	v_fma_f32 v156, v72, v72, -1.0
	v_cmp_lt_f32_e32 vcc, s76, v57
	v_mul_f32_e32 v71, v56, v71
	s_waitcnt lgkmcnt(0)
; __device__ __forceinline__ float bf2f(bf16_t b) { return __uint_as_float(((unsigned)b) << 16); }
; __device__ __forceinline__ float fast_sigmoid(float x) { return __builtin_amdgcn_rcpf(1.0f + __builtin_amdgcn_exp2f(-1.4426950408889634f * x)); }
; template <int DIR>
; __device__ __forceinline__ void scan_dir(PP p, const bf16_t* xs, const ScanW& w, ScanW& wn, int ndir, int nct, bool do_next, int n, int ct, int l31, int hl, int id, int rowbase, bool latent, float (&hf)[2][16]) {
;     ...
;         for (int i = 0; i < 16; ++i) {
;             const int token = 32 * rt + 8 * (i >> 2) + 4 * hl + (i & 3);
;             const float xv = bf2f(xs[token * XS + ch]);
;             const float rr = fast_sigmoid(ga[i] + ba), ii = fast_sigmoid(gi[i] + bi);
;             const float la2 = rr * sp8l2;
;             const float av = __builtin_amdgcn_exp2f(la2);
;             const float t2 = la2 * 1.3862943611f;
;             float em1p = t2 * (1.0f + t2 * (0.5f + t2 * (0.16666667f + t2 * (0.041666668f + t2 * 0.0083333333f)))), em1e = __builtin_fmaf(av, av, -1.0f);
;             asm volatile("" : "+v"(em1p), "+v"(em1e));
;             const float em1 = (t2 > -0.1f) ? em1p : em1e;
;             a[rt][i] = av; u[rt][i] = __builtin_amdgcn_sqrtf(-em1) * (ii * xv);
;         }
	v_lshlrev_b32_e32 v56, 16, v131
	v_cndmask_b32_e32 v57, v156, v155, vcc
	v_sqrt_f32_e64 v57, -v57
	v_mul_f32_e32 v56, v154, v56
	v_add_f32_e32 v60, v189, v60
	v_mul_f32_e32 v60, 0xbfb8aa3b, v60
	v_mul_f32_e32 v73, v57, v56
	v_add_f32_e32 v57, v189, v58
	v_add_f32_e32 v58, v190, v74
	v_mul_f32_e32 v58, 0xbfb8aa3b, v58
	v_exp_f32_e32 v58, v58
	v_mul_f32_e32 v57, 0xbfb8aa3b, v57
	v_exp_f32_e32 v57, v57
	s_waitcnt lgkmcnt(0)
	v_lshlrev_b32_e32 v74, 16, v132
	v_add_f32_e32 v56, 1.0, v58
	v_rcp_f32_e32 v58, v56
	v_add_f32_e32 v57, 1.0, v57
	v_rcp_f32_e32 v57, v57
	v_exp_f32_e32 v60, v60
	v_mul_f32_e32 v74, v58, v74
	v_add_f32_e32 v58, v189, v59
	v_mul_f32_e32 v58, 0xbfb8aa3b, v58
	v_exp_f32_e32 v58, v58
	v_mul_f32_e32 v57, v193, v57
	v_exp_f32_e32 v56, v57
	v_mul_f32_e32 v57, 0x3fb17218, v57
	v_fmamk_f32 v154, v57, 0x3c088888, v186
	v_fmaak_f32 v154, v57, v154, 0x3e2aaaab
	v_add_f32_e32 v58, 1.0, v58
	v_fma_f32 v154, v57, v154, 0.5
	v_add_f32_e32 v59, v190, v75
	v_rcp_f32_e32 v58, v58
	v_fma_f32 v154, v57, v154, 1.0
	v_mul_f32_e32 v59, 0xbfb8aa3b, v59
	v_mul_f32_e32 v154, v57, v154
	v_fma_f32 v155, v56, v56, -1.0
	v_exp_f32_e32 v59, v59
	v_cmp_lt_f32_e32 vcc, s76, v57
	v_add_f32_e32 v59, 1.0, v59
	v_cndmask_b32_e32 v57, v155, v154, vcc
	v_mul_f32_e32 v154, v193, v58
	v_exp_f32_e32 v58, v154
	v_mul_f32_e32 v154, 0x3fb17218, v154
	v_sqrt_f32_e64 v57, -v57
	v_fmamk_f32 v155, v154, 0x3c088888, v186
	v_rcp_f32_e32 v59, v59
	v_fmaak_f32 v155, v154, v155, 0x3e2aaaab
	v_fma_f32 v155, v154, v155, 0.5
	v_fma_f32 v155, v154, v155, 1.0
	v_mul_f32_e32 v155, v154, v155
	v_fma_f32 v156, v58, v58, -1.0
	v_mul_f32_e32 v57, v57, v74
	s_waitcnt lgkmcnt(0)
	v_lshlrev_b32_e32 v74, 16, v133
	v_add_f32_e32 v75, v190, v76
	v_mul_f32_e32 v59, v59, v74
	v_mul_f32_e32 v75, 0xbfb8aa3b, v75
	v_exp_f32_e32 v75, v75
	v_add_f32_e32 v60, 1.0, v60
	v_cmp_lt_f32_e32 vcc, s76, v154
	v_rcp_f32_e32 v60, v60
	s_waitcnt lgkmcnt(0)
	v_lshlrev_b32_e32 v76, 16, v134
	v_add_f32_e32 v74, 1.0, v75
	v_add_f32_e32 v61, v189, v61
	v_cndmask_b32_e32 v154, v156, v155, vcc
	v_rcp_f32_e32 v75, v74
	v_mul_f32_e32 v61, 0xbfb8aa3b, v61
	v_sqrt_f32_e64 v154, -v154
	v_exp_f32_e32 v61, v61
	v_mul_f32_e32 v60, v193, v60
	v_exp_f32_e32 v74, v60
	v_mul_f32_e32 v60, 0x3fb17218, v60
	v_mul_f32_e32 v75, v75, v76
	v_add_f32_e32 v76, v190, v77
	v_mul_f32_e32 v59, v154, v59
	v_fmamk_f32 v154, v60, 0x3c088888, v186
	v_mul_f32_e32 v76, 0xbfb8aa3b, v76
	v_add_f32_e32 v61, 1.0, v61
	v_fmaak_f32 v154, v60, v154, 0x3e2aaaab
	v_exp_f32_e32 v76, v76
	v_rcp_f32_e32 v61, v61
	v_fma_f32 v154, v60, v154, 0.5
	v_fma_f32 v154, v60, v154, 1.0
	v_mul_f32_e32 v154, v60, v154
	v_fma_f32 v155, v74, v74, -1.0
	v_cmp_lt_f32_e32 vcc, s76, v60
	v_add_f32_e32 v76, 1.0, v76
	v_mul_f32_e32 v61, v193, v61
	v_cndmask_b32_e32 v60, v155, v154, vcc
	v_rcp_f32_e32 v154, v76
	v_exp_f32_e32 v76, v61
	v_mul_f32_e32 v61, 0x3fb17218, v61
	v_fmamk_f32 v155, v61, 0x3c088888, v186
	v_fmaak_f32 v155, v61, v155, 0x3e2aaaab
	v_fma_f32 v155, v61, v155, 0.5
	v_fma_f32 v155, v61, v155, 1.0
	v_sqrt_f32_e64 v60, -v60
	v_mul_f32_e32 v155, v61, v155
	v_fma_f32 v156, v76, v76, -1.0
	v_cmp_lt_f32_e32 vcc, s76, v61
	v_mul_f32_e32 v75, v60, v75
	s_waitcnt lgkmcnt(0)
	v_lshlrev_b32_e32 v60, 16, v135
	v_cndmask_b32_e32 v61, v156, v155, vcc
	v_sqrt_f32_e64 v61, -v61
	v_mul_f32_e32 v60, v154, v60
	v_add_f32_e32 v64, v189, v64
	v_mul_f32_e32 v64, 0xbfb8aa3b, v64
	v_mul_f32_e32 v77, v61, v60
	v_add_f32_e32 v61, v189, v62
	v_add_f32_e32 v62, v190, v78
	v_mul_f32_e32 v62, 0xbfb8aa3b, v62
	v_mul_f32_e32 v61, 0xbfb8aa3b, v61
	v_exp_f32_e32 v62, v62
	v_exp_f32_e32 v61, v61
	s_waitcnt lgkmcnt(0)
	v_lshlrev_b32_e32 v78, 16, v136
	v_exp_f32_e32 v64, v64
	v_add_f32_e32 v60, 1.0, v62
	v_add_f32_e32 v61, 1.0, v61
	v_rcp_f32_e32 v62, v60
	v_rcp_f32_e32 v61, v61
	v_add_f32_e32 v65, v189, v65
	v_mul_f32_e32 v65, 0xbfb8aa3b, v65
	v_mul_f32_e32 v78, v62, v78
	v_add_f32_e32 v62, v189, v63
	v_mul_f32_e32 v61, v193, v61
	v_mul_f32_e32 v62, 0xbfb8aa3b, v62
	v_exp_f32_e32 v60, v61
	v_mul_f32_e32 v61, 0x3fb17218, v61
	v_exp_f32_e32 v62, v62
	v_fmamk_f32 v154, v61, 0x3c088888, v186
	v_fmaak_f32 v154, v61, v154, 0x3e2aaaab
	v_fma_f32 v154, v61, v154, 0.5
	v_fma_f32 v154, v61, v154, 1.0
	v_add_f32_e32 v62, 1.0, v62
	v_mul_f32_e32 v154, v61, v154
	v_fma_f32 v155, v60, v60, -1.0
	v_cmp_lt_f32_e32 vcc, s76, v61
	v_add_f32_e32 v63, v190, v79
	v_rcp_f32_e32 v62, v62
	v_mul_f32_e32 v63, 0xbfb8aa3b, v63
	v_cndmask_b32_e32 v61, v155, v154, vcc
	v_sqrt_f32_e64 v61, -v61
	v_exp_f32_e32 v63, v63
	v_mul_f32_e32 v154, v193, v62
	v_exp_f32_e32 v62, v154
	v_mul_f32_e32 v154, 0x3fb17218, v154
	v_add_f32_e32 v63, 1.0, v63
	v_fmamk_f32 v155, v154, 0x3c088888, v186
	v_mul_f32_e32 v61, v61, v78
	s_waitcnt lgkmcnt(0)
; __device__ __forceinline__ float bf2f(bf16_t b) { return __uint_as_float(((unsigned)b) << 16); }
; __device__ __forceinline__ void scan_loadw(PP p, int dir, int n, int ct, int l31, int hl, ScanW& w) {
;     unsigned chv = (unsigned)(32 * ct + l31); asm volatile("" : "+v"(chv));
;     const unsigned ch = (unsigned)(dir * 512 + 64 * n) + chv;
;     w.ba = p->lru_b_a[ch]; w.bi = p->lru_b_i[ch];
;     w.sp8l2 = ((const float*)(p->ws + WS_SP8))[ch] * 1.4426950408889634f;
;     const bf16_t* wa_b = (const bf16_t*)(p->ws + WS_LRU) + (size_t)((dir * 2 + 0) * 8 + n) * 4096;
;     const bf16_t* wi_b = (const bf16_t*)(p->ws + WS_LRU) + (size_t)((dir * 2 + 1) * 8 + n) * 4096;
;     const unsigned lo = chv * 64u + 8u * (unsigned)hl;
; #pragma unroll
;     for (int st = 0; st < 4; ++st) { w.wfa[st] = *(const bf16x8*)(wa_b + lo + 16 * st); w.wfi[st] = *(const bf16x8*)(wi_b + lo + 16 * st); }
; template <int DIR>
; __device__ __forceinline__ void scan_dir(PP p, const bf16_t* xs, const ScanW& w, ScanW& wn, int ndir, int nct, bool do_next, int n, int ct, int l31, int hl, int id, int rowbase, bool latent, float (&hf)[2][16]) {
;     ...
;         for (int i = 0; i < 16; ++i) {
;             const int token = 32 * rt + 8 * (i >> 2) + 4 * hl + (i & 3);
;             const float xv = bf2f(xs[token * XS + ch]);
;             const float rr = fast_sigmoid(ga[i] + ba), ii = fast_sigmoid(gi[i] + bi);
;             const float la2 = rr * sp8l2;
;             const float av = __builtin_amdgcn_exp2f(la2);
;             const float t2 = la2 * 1.3862943611f;
;             float em1p = t2 * (1.0f + t2 * (0.5f + t2 * (0.16666667f + t2 * (0.041666668f + t2 * 0.0083333333f)))), em1e = __builtin_fmaf(av, av, -1.0f);
;             asm volatile("" : "+v"(em1p), "+v"(em1e));
;             const float em1 = (t2 > -0.1f) ? em1p : em1e;
;             a[rt][i] = av; u[rt][i] = __builtin_amdgcn_sqrtf(-em1) * (ii * xv);
;         }
;     }
;     float Ao[8], Ho[8], Ap[8], Hp[8];
; #pragma unroll
;     for (int k = 0; k < 8; ++k) {
;         const int rt = k >> 2, g = k & 3;
;         float H = 0.f, A = 1.f;
; #pragma unroll
;         for (int jj = 0; jj < 4; ++jj) { const int j = DIR ? 3 - jj : jj; const float av = a[rt][4 * g + j]; H = av * H + u[rt][4 * g + j]; A *= av; }
;         Ao[k] = A; Ho[k] = H; Ap[k] = __shfl_xor(A, 32); Hp[k] = __shfl_xor(H, 32);
;     }
	v_lshlrev_b32_e32 v78, 16, v137
	v_add_f32_e32 v79, v190, v80
	v_rcp_f32_e32 v63, v63
	v_fmaak_f32 v155, v154, v155, 0x3e2aaaab
	v_mul_f32_e32 v79, 0xbfb8aa3b, v79
	v_fma_f32 v155, v154, v155, 0.5
	v_exp_f32_e32 v79, v79
	v_exp_f32_e32 v65, v65
	v_fma_f32 v155, v154, v155, 1.0
	v_mul_f32_e32 v155, v154, v155
	v_fma_f32 v156, v62, v62, -1.0
	v_add_f32_e32 v64, 1.0, v64
	v_cmp_lt_f32_e32 vcc, s76, v154
	v_mul_f32_e32 v63, v63, v78
	v_rcp_f32_e32 v64, v64
	v_cndmask_b32_e32 v154, v156, v155, vcc
	v_add_f32_e32 v79, 1.0, v79
	v_add_f32_e32 v65, 1.0, v65
	v_sqrt_f32_e64 v154, -v154
	v_rcp_f32_e32 v79, v79
	v_rcp_f32_e32 v65, v65
	v_mul_f32_e32 v80, v193, v64
	s_waitcnt lgkmcnt(0)
	v_lshlrev_b32_e32 v78, 16, v138
	v_exp_f32_e32 v64, v80
	v_mul_f32_e32 v80, 0x3fb17218, v80
	v_fma_f32 v156, 0, v205, v211
	v_mul_f32_e32 v63, v154, v63
	v_fmamk_f32 v154, v80, 0x3c088888, v186
	v_mul_f32_e32 v78, v79, v78
	v_add_f32_e32 v79, v190, v81
	v_mul_f32_e32 v65, v193, v65
	v_fma_f32 v156, v204, v156, v208
	v_fmaak_f32 v154, v80, v154, 0x3e2aaaab
	v_mul_f32_e32 v79, 0xbfb8aa3b, v79
	v_exp_f32_e32 v213, v65
	v_mul_f32_e32 v65, 0x3fb17218, v65
	v_fma_f32 v156, v42, v156, v43
	v_fma_f32 v154, v80, v154, 0.5
	v_exp_f32_e32 v79, v79
	v_fmamk_f32 v81, v65, 0x3c088888, v186
	v_fma_f32 v216, v40, v156, v41
	v_fma_f32 v156, 0, v207, v210
	v_fma_f32 v154, v80, v154, 1.0
	v_fmaak_f32 v81, v65, v81, 0x3e2aaaab
	v_fma_f32 v156, v206, v156, v209
	v_mul_f32_e32 v154, v80, v154
	v_fma_f32 v155, v64, v64, -1.0
	v_fma_f32 v81, v65, v81, 0.5
	v_fma_f32 v156, v45, v156, v48
	v_cmp_lt_f32_e32 vcc, s76, v80
	ds_read_u16 v0, v0 offset:61360
	v_fma_f32 v81, v65, v81, 1.0
	v_fma_f32 v221, v44, v156, v47
	v_fma_f32 v156, 0, v68, v69
	v_cndmask_b32_e32 v80, v155, v154, vcc
	v_add_f32_e32 v79, 1.0, v79
	v_mul_f32_e32 v81, v65, v81
	v_fma_f32 v154, v213, v213, -1.0
	v_cmp_lt_f32_e32 vcc, s76, v65
	v_fma_f32 v156, v66, v156, v67
	v_rcp_f32_e32 v79, v79
	v_fma_f32 v156, v50, v156, v51
	v_cndmask_b32_e32 v65, v154, v81, vcc
	v_sqrt_f32_e64 v65, -v65
	v_mul_f32_e32 v158, v45, v158
	v_fma_f32 v225, v46, v156, v49
	v_fma_f32 v156, 0, v72, v73
	v_mul_f32_e32 v222, v44, v158
	v_mul_f32_e32 v158, v68, v66
	v_fma_f32 v156, v70, v156, v71
	v_sqrt_f32_e64 v80, -v80
	s_waitcnt lgkmcnt(0)
	v_lshlrev_b32_e32 v0, 16, v0
	v_mul_f32_e32 v158, v50, v158
	v_fma_f32 v156, v54, v156, v55
	v_mul_f32_e32 v0, v79, v0
	v_mul_f32_e32 v226, v46, v158
	v_mul_f32_e32 v158, v72, v70
	v_fma_f32 v229, v52, v156, v53
	v_fma_f32 v156, 0, v76, v77
	v_mul_f32_e32 v214, v65, v0
	v_and_b32_e32 v65, 64, v188
	v_mul_f32_e32 v158, v54, v158
	v_fma_f32 v156, v74, v156, v75
	v_xor_b32_e32 v0, 32, v188
	v_add_u32_e32 v65, 64, v65
	v_mul_f32_e32 v230, v52, v158
	v_mul_f32_e32 v158, v76, v74
	v_fma_f32 v156, v58, v156, v59
	v_mul_f32_e32 v81, v80, v78
	v_cmp_lt_i32_e32 vcc, v0, v65
	v_fma_f32 v65, 0, v198, v199
	v_fma_f32 v154, 0, v202, v203
	v_mul_f32_e32 v158, v58, v158
	v_fma_f32 v233, v56, v156, v57
	v_fma_f32 v156, 0, v213, v214
	v_fma_f32 v65, v196, v65, v197
	v_mul_f32_e32 v78, v198, v196
	v_fma_f32 v154, v200, v154, v201
	v_mul_f32_e32 v155, v202, v200
	v_mul_f32_e32 v234, v56, v158
	v_fma_f32 v156, v64, v156, v81
	v_mul_f32_e32 v158, v213, v64
	v_cndmask_b32_e32 v0, v188, v0, vcc
	v_fma_f32 v65, v147, v65, v195
	v_mul_f32_e32 v78, v147, v78
	v_fma_f32 v154, v38, v154, v39
	v_mul_f32_e32 v155, v38, v155
	v_fma_f32 v156, v62, v156, v63
	v_mul_f32_e32 v159, v62, v158
	v_lshlrev_b32_e32 v0, 2, v0
	v_fma_f32 v65, v34, v65, v35
	v_mul_f32_e32 v78, v34, v78
	v_fma_f32 v154, v36, v154, v37
	v_mul_f32_e32 v155, v36, v155
	v_fma_f32 v158, v60, v156, v61
	v_mul_f32_e32 v156, v60, v159
	ds_bpermute_b32 v79, v0, v78
	ds_bpermute_b32 v80, v0, v65
	ds_bpermute_b32 v212, v0, v155
	ds_bpermute_b32 v215, v0, v154
	ds_bpermute_b32 v218, v0, v217
	ds_bpermute_b32 v219, v0, v216
	ds_bpermute_b32 v223, v0, v222
	ds_bpermute_b32 v224, v0, v221
	ds_bpermute_b32 v227, v0, v226
	ds_bpermute_b32 v228, v0, v225
	ds_bpermute_b32 v231, v0, v230
	ds_bpermute_b32 v232, v0, v229
	ds_bpermute_b32 v235, v0, v234
	ds_bpermute_b32 v236, v0, v233
	ds_bpermute_b32 v220, v0, v156
	ds_bpermute_b32 v237, v0, v158
	s_andn2_b64 vcc, exec, s[4:5]
	s_cbranch_vccnz .LBB0_447
	v_or_b32_e32 v118, 32, v148
	s_load_dwordx2 s[4:5], s[8:9], 0x58
	s_load_dwordx2 s[44:45], s[8:9], 0x68
	v_add_u32_e32 v0, s33, v118
	v_lshlrev_b64 v[114:115], 2, v[0:1]
	v_lshl_or_b32 v0, v118, 6, v149
	s_waitcnt lgkmcnt(0)
	v_lshl_add_u64 v[116:117], s[4:5], 0, v[114:115]
	global_load_dword v192, v[116:117], off
	v_lshl_add_u64 v[116:117], s[44:45], 0, v[114:115]
	global_load_dword v191, v[116:117], off
	v_lshlrev_b64 v[116:117], 1, v[0:1]
	v_lshl_add_u64 v[114:115], s[12:13], 0, v[114:115]
	v_lshl_add_u64 v[138:139], s[14:15], 0, v[116:117]
	v_lshl_add_u64 v[142:143], s[18:19], 0, v[116:117]
	global_load_dword v0, v[114:115], off
	s_nop 0
	global_load_dwordx4 v[114:117], v[138:139], off
	global_load_dwordx4 v[118:121], v[138:139], off offset:32
	global_load_dwordx4 v[122:125], v[138:139], off offset:64
	global_load_dwordx4 v[126:129], v[142:143], off offset:32
	global_load_dwordx4 v[130:133], v[142:143], off offset:64
	global_load_dwordx4 v[134:137], v[142:143], off
	s_nop 0
	global_load_dwordx4 v[138:141], v[138:139], off offset:96
	s_nop 0
	global_load_dwordx4 v[142:145], v[142:143], off offset:96
	s_waitcnt vmcnt(8)
	v_mul_f32_e32 v194, 0x3fb8aa3b, v0
